# v32 + PLE epilogue: each row group's second-half loads (LO/HI/PP +256 B) issued right after its first-half loads into GEMM-dead VGPRs (one memory round trip per row group instead of two)
# baseline (speedup 1.0000x reference)
; __device__ __forceinline__ float row_ssq(const float* part, int pitch, int n4, int row, int fq) {
;     __device__ __forceinline__ void operator()(const f32x4 (&acc)[2][2][4][2], const Unit& u, int wr, int wc, int fr, int fq) const {
;     ...
;                 const int row = row0 + ai * HALF + m * 16;
;                 float rs = 0.f; if (GATED) rs = rsqrtf(row_ssq(ssq_in, 16, 4, row, fq) * (1.f / 1024.f) + EPS);
;                 float sq = 0.f;
; #pragma unroll
;                 for (int bj = 0; bj < 2; ++bj) {
;                     const size_t off = (size_t)row * DM + col0 + bj * HALF;
;                     const u32x4 hh = *(const u32x4*)(HI + off), ll = *(const u32x4*)(LO + off);
;                     float hv[8] = {bflo(hh.x) + bflo(ll.x), bfhi(hh.x) + bfhi(ll.x), bflo(hh.y) + bflo(ll.y), bfhi(hh.y) + bfhi(ll.y),
;                                    bflo(hh.z) + bflo(ll.z), bfhi(hh.z) + bfhi(ll.z), bflo(hh.w) + bflo(ll.w), bfhi(hh.w) + bfhi(ll.w)};
;                     float av[8] = {acc[ai][bj][m][0][0], acc[ai][bj][m][0][1], acc[ai][bj][m][0][2], acc[ai][bj][m][0][3], acc[ai][bj][m][1][0], acc[ai][bj][m][1][1], acc[ai][bj][m][1][2], acc[ai][bj][m][1][3]};
;                     if (GATED) { const u32x4 pp = *(const u32x4*)(PP + off);
;                         const float pv[8] = {bflo(pp.x), bfhi(pp.x), bflo(pp.y), bfhi(pp.y), bflo(pp.z), bfhi(pp.z), bflo(pp.w), bfhi(pp.w)};
; #pragma unroll
;                         for (int e = 0; e < 8; ++e) av[e] = fast_sigmoid(av[e] * rs) * pv[e]; }
;                     else {
; #pragma unroll
;                         for (int e = 0; e < 8; ++e) av[e] *= alpha; }
;                     float lo[8];
; #pragma unroll
;                     for (int e = 0; e < 8; ++e) { hv[e] += av[e]; sq += hv[e] * hv[e]; }
;                     u32x4 wh; wh.x = pk2(hv[0], hv[1]); wh.y = pk2(hv[2], hv[3]); wh.z = pk2(hv[4], hv[5]); wh.w = pk2(hv[6], hv[7]);
;                     lo[0] = hv[0] - bflo(wh.x); lo[1] = hv[1] - bfhi(wh.x); lo[2] = hv[2] - bflo(wh.y); lo[3] = hv[3] - bfhi(wh.y);
;                     lo[4] = hv[4] - bflo(wh.z); lo[5] = hv[5] - bfhi(wh.z); lo[6] = hv[6] - bflo(wh.w); lo[7] = hv[7] - bfhi(wh.w);
;                     u32x4 wl; wl.x = pk2(lo[0], lo[1]); wl.y = pk2(lo[2], lo[3]); wl.z = pk2(lo[4], lo[5]); wl.w = pk2(lo[6], lo[7]);
;                     *(u32x4*)(HO + off) = wh; *(u32x4*)(LO + off) = wl;
.LBB0_1338:
	v_lshl_add_u32 v144, s27, 8, v154
	v_ashrrev_i32_e32 v145, 31, v144
	v_lshlrev_b64 v[146:147], 6, v[144:145]
	v_lshl_add_u64 v[148:149], v[136:137], 0, v[146:147]
	global_load_dwordx4 v[150:153], v[148:149], off
	v_lshl_or_b32 v142, s4, 8, v156
	v_ashrrev_i32_e32 v143, 31, v142
	v_lshlrev_b64 v[148:149], 10, v[144:145]
	v_lshl_add_u64 v[148:149], v[148:149], 0, v[142:143]
	v_readlane_b32 s10, v253, 35
	v_lshlrev_b64 v[148:149], 1, v[148:149]
	v_readlane_b32 s11, v253, 36
	v_readlane_b32 s14, v250, 47
	v_readlane_b32 s15, v250, 48
	v_lshl_add_u64 v[158:159], s[10:11], 0, v[148:149]
	global_load_dwordx4 v[160:163], v[158:159], off
	v_lshl_add_u64 v[158:159], s[14:15], 0, v[148:149]
	global_load_dwordx4 v[168:171], v[158:159], off
	v_readlane_b32 s6, v250, 49
	v_readlane_b32 s7, v250, 50
	v_and_b32_e32 v158, 64, v241
	v_xor_b32_e32 v145, 16, v241
	v_lshl_add_u64 v[172:173], s[6:7], 0, v[148:149]
	global_load_dwordx4 v[164:167], v[172:173], off
	global_load_dwordx4 v[234:237], v148, s[6:7] offset:256
	global_load_dwordx4 v[226:229], v148, s[10:11] offset:256
	global_load_dwordx4 v[230:233], v148, s[14:15] offset:256
	v_add_u32_e32 v158, 64, v158
	v_xor_b32_e32 v159, 32, v241
	v_cmp_lt_i32_e32 vcc, v145, v158
	s_lshl_b32 s54, s4, 2
	s_mov_b32 s16, 0x800000
	v_cndmask_b32_e32 v145, v241, v145, vcc
	v_cmp_lt_i32_e32 vcc, v159, v158
	v_lshlrev_b32_e32 v158, 2, v145
	s_waitcnt vmcnt(3)
	v_mov_b32_e32 v174, v151
	v_mov_b32_e32 v175, v152
	v_mov_b32_e32 v151, v153
	v_cndmask_b32_e32 v159, v241, v159, vcc
	v_pk_add_f32 v[150:151], v[174:175], v[150:151]
	v_lshlrev_b32_e32 v145, 2, v159
	v_add_f32_e32 v159, v150, v151
	v_mov_b32_e32 v182, v159
	s_nop 1
	v_permlane16_swap_b32_e32 v159, v182
	v_lshlrev_b32_e32 v150, 16, v160
	s_waitcnt lgkmcnt(0)
	v_add_f32_e32 v159, v159, v182
	v_lshlrev_b32_e32 v180, 16, v170
	v_and_b32_e32 v181, 0xffff0000, v170
	v_mov_b32_e32 v170, v159
	s_nop 1
	v_permlane32_swap_b32_e32 v159, v170
	v_and_b32_e32 v151, 0xffff0000, v160
	v_lshlrev_b32_e32 v160, 16, v161
	v_and_b32_e32 v161, 0xffff0000, v161
	v_lshlrev_b32_e32 v152, 16, v164
	v_and_b32_e32 v153, 0xffff0000, v164
	v_pk_add_f32 v[150:151], v[150:151], v[152:153]
	s_waitcnt lgkmcnt(0)
	v_add_f32_e32 v152, v159, v170
	v_fmamk_f32 v152, v152, 0x3a800000, v239
	v_mul_f32_e32 v153, 0x4b800000, v152
	v_cmp_gt_f32_e32 vcc, s55, v152
	v_lshlrev_b32_e32 v164, 16, v165
	v_and_b32_e32 v165, 0xffff0000, v165
	v_cndmask_b32_e32 v152, v152, v153, vcc
	v_rsq_f32_e32 v159, v152
	v_pk_add_f32 v[152:153], v[160:161], v[164:165]
	v_lshlrev_b32_e32 v176, 16, v162
	v_and_b32_e32 v177, 0xffff0000, v162
	v_mul_f32_e32 v164, 0x45800000, v159
	v_cndmask_b32_e32 v159, v159, v164, vcc
	v_mul_f32_e32 v128, v128, v159
	v_mul_f32_e32 v129, v129, v159
	v_mul_f32_e32 v126, v126, v159
	v_mul_f32_e32 v127, v127, v159
	v_mul_f32_e32 v122, v122, v159
	v_mul_f32_e32 v123, v123, v159
	v_mul_f32_e32 v124, v124, v159
	v_mul_f32_e32 v125, v125, v159
	v_mul_f32_e32 v128, 0xbfb8aa3b, v128
	v_mul_f32_e32 v129, 0xbfb8aa3b, v129
	v_mul_f32_e32 v126, 0xbfb8aa3b, v126
	v_mul_f32_e32 v127, 0xbfb8aa3b, v127
	v_mul_f32_e32 v122, 0xbfb8aa3b, v122
	v_mul_f32_e32 v123, 0xbfb8aa3b, v123
	v_mul_f32_e32 v124, 0xbfb8aa3b, v124
	v_mul_f32_e32 v125, 0xbfb8aa3b, v125
	v_exp_f32_e32 v128, v128
	v_exp_f32_e32 v129, v129
	v_exp_f32_e32 v126, v126
	v_exp_f32_e32 v127, v127
	v_exp_f32_e32 v122, v122
	v_exp_f32_e32 v123, v123
	v_exp_f32_e32 v124, v124
	v_exp_f32_e32 v125, v125
	v_lshlrev_b32_e32 v178, 16, v166
	v_and_b32_e32 v179, 0xffff0000, v166
	v_lshlrev_b32_e32 v162, 16, v163
	v_and_b32_e32 v163, 0xffff0000, v163
	v_lshlrev_b32_e32 v166, 16, v167
	v_and_b32_e32 v167, 0xffff0000, v167
	v_add_f32_e32 v128, 1.0, v128
	v_add_f32_e32 v129, 1.0, v129
	v_pk_add_f32 v[162:163], v[162:163], v[166:167]
	v_add_f32_e32 v126, 1.0, v126
	v_add_f32_e32 v127, 1.0, v127
	v_add_f32_e32 v164, 1.0, v122
	v_add_f32_e32 v165, 1.0, v123
	v_add_f32_e32 v166, 1.0, v124
	v_add_f32_e32 v167, 1.0, v125
	v_rcp_f32_e32 v124, v128
	v_rcp_f32_e32 v125, v129
	v_rcp_f32_e32 v122, v126
	v_rcp_f32_e32 v123, v127
	v_rcp_f32_e32 v126, v164
	v_rcp_f32_e32 v127, v165
	v_rcp_f32_e32 v128, v166
	v_rcp_f32_e32 v129, v167
	v_lshlrev_b32_e32 v174, 16, v168
	v_and_b32_e32 v175, 0xffff0000, v168
	v_lshlrev_b32_e32 v168, 16, v169
	v_and_b32_e32 v169, 0xffff0000, v169
	v_pk_add_f32 v[160:161], v[176:177], v[178:179]
	v_pk_fma_f32 v[166:167], v[124:125], v[168:169], v[152:153]
	v_lshlrev_b32_e32 v168, 16, v171
	v_and_b32_e32 v169, 0xffff0000, v171
	v_pk_fma_f32 v[164:165], v[122:123], v[174:175], v[150:151]
	v_pk_fma_f32 v[160:161], v[126:127], v[180:181], v[160:161]
	v_pk_fma_f32 v[162:163], v[128:129], v[168:169], v[162:163]
	v_cvt_pk_bf16_f32 v122, v164, v165
	v_cvt_pk_bf16_f32 v123, v166, v167
	v_cvt_pk_bf16_f32 v124, v160, v161
	v_cvt_pk_bf16_f32 v125, v162, v163
	v_lshlrev_b32_e32 v126, 16, v122
	v_and_b32_e32 v127, 0xffff0000, v122
	v_lshlrev_b32_e32 v150, 16, v123
	v_and_b32_e32 v151, 0xffff0000, v123
	v_lshlrev_b32_e32 v152, 16, v124
	v_and_b32_e32 v153, 0xffff0000, v124
	v_lshlrev_b32_e32 v128, 16, v125
	v_and_b32_e32 v129, 0xffff0000, v125
	v_pk_add_f32 v[126:127], v[164:165], v[126:127] neg_lo:[0,1] neg_hi:[0,1]
	v_pk_add_f32 v[150:151], v[166:167], v[150:151] neg_lo:[0,1] neg_hi:[0,1]
	v_pk_add_f32 v[152:153], v[160:161], v[152:153] neg_lo:[0,1] neg_hi:[0,1]
	v_pk_add_f32 v[168:169], v[162:163], v[128:129] neg_lo:[0,1] neg_hi:[0,1]
	v_cvt_pk_bf16_f32 v126, v126, v127
	v_cvt_pk_bf16_f32 v127, v150, v151
	v_cvt_pk_bf16_f32 v128, v152, v153
	v_lshl_add_u64 v[150:151], s[58:59], 0, v[148:149]
	v_or_b32_e32 v148, 0x100, v148
	v_cvt_pk_bf16_f32 v129, v168, v169
	global_store_dwordx4 v[150:151], v[122:125], off
	v_lshl_add_u64 v[170:171], s[6:7], 0, v[148:149]
	global_store_dwordx4 v[172:173], v[126:129], off
	s_waitcnt vmcnt(4)
; __device__ __forceinline__ float bflo(unsigned u) { return __uint_as_float(u << 16); }
;     __device__ __forceinline__ void operator()(const f32x4 (&acc)[2][2][4][2], const Unit& u, int wr, int wc, int fr, int fq) const {
;     ...
;                 for (int bj = 0; bj < 2; ++bj) {
;                     const size_t off = (size_t)row * DM + col0 + bj * HALF;
;                     const u32x4 hh = *(const u32x4*)(HI + off), ll = *(const u32x4*)(LO + off);
;                     float hv[8] = {bflo(hh.x) + bflo(ll.x), bfhi(hh.x) + bfhi(ll.x), bflo(hh.y) + bflo(ll.y), bfhi(hh.y) + bfhi(ll.y),
;                                    bflo(hh.z) + bflo(ll.z), bfhi(hh.z) + bfhi(ll.z), bflo(hh.w) + bflo(ll.w), bfhi(hh.w) + bfhi(ll.w)};
;                     float av[8] = {acc[ai][bj][m][0][0], acc[ai][bj][m][0][1], acc[ai][bj][m][0][2], acc[ai][bj][m][0][3], acc[ai][bj][m][1][0], acc[ai][bj][m][1][1], acc[ai][bj][m][1][2], acc[ai][bj][m][1][3]};
;                     if (GATED) { const u32x4 pp = *(const u32x4*)(PP + off);
;                         const float pv[8] = {bflo(pp.x), bfhi(pp.x), bflo(pp.y), bfhi(pp.y), bflo(pp.z), bfhi(pp.z), bflo(pp.w), bfhi(pp.w)};
; #pragma unroll
;                         for (int e = 0; e < 8; ++e) av[e] = fast_sigmoid(av[e] * rs) * pv[e]; }
;                     else {
; #pragma unroll
;                         for (int e = 0; e < 8; ++e) av[e] *= alpha; }
;                     float lo[8];
; #pragma unroll
;                     for (int e = 0; e < 8; ++e) { hv[e] += av[e]; sq += hv[e] * hv[e]; }
;                     u32x4 wh; wh.x = pk2(hv[0], hv[1]); wh.y = pk2(hv[2], hv[3]); wh.z = pk2(hv[4], hv[5]); wh.w = pk2(hv[6], hv[7]);
;                     lo[0] = hv[0] - bflo(wh.x); lo[1] = hv[1] - bfhi(wh.x); lo[2] = hv[2] - bflo(wh.y); lo[3] = hv[3] - bfhi(wh.y);
;                     lo[4] = hv[4] - bflo(wh.z); lo[5] = hv[5] - bfhi(wh.z); lo[6] = hv[6] - bflo(wh.w); lo[7] = hv[7] - bfhi(wh.w);
;                     u32x4 wl; wl.x = pk2(lo[0], lo[1]); wl.y = pk2(lo[2], lo[3]); wl.z = pk2(lo[4], lo[5]); wl.w = pk2(lo[6], lo[7]);
;                     *(u32x4*)(HO + off) = wh; *(u32x4*)(LO + off) = wl;
;                 }
;                 sq += __shfl_xor(sq, 16); sq += __shfl_xor(sq, 32);
;                 if (fq == 0) ssq_out[(size_t)row * 16 + 4 * u.pn + wc] = sq;
	s_nop 0
	v_mov_b32_e32 v122, v234
	v_mov_b32_e32 v123, v235
	v_mov_b32_e32 v124, v236
	v_mov_b32_e32 v125, v237
	v_lshl_add_u64 v[150:151], s[14:15], 0, v[148:149]
	v_lshl_add_u64 v[126:127], s[10:11], 0, v[148:149]
	s_waitcnt vmcnt(3)
	s_nop 0
	v_mov_b32_e32 v126, v226
	v_mov_b32_e32 v127, v227
	v_mov_b32_e32 v128, v228
	v_mov_b32_e32 v129, v229
	v_mul_f32_e32 v118, v118, v159
	s_waitcnt vmcnt(2)
	s_nop 0
	v_mov_b32_e32 v150, v230
	v_mov_b32_e32 v151, v231
	v_mov_b32_e32 v152, v232
	v_mov_b32_e32 v153, v233
	v_mul_f32_e32 v119, v119, v159
	v_mul_f32_e32 v120, v120, v159
	v_mul_f32_e32 v121, v121, v159
	v_mul_f32_e32 v114, v114, v159
	v_mul_f32_e32 v115, v115, v159
	v_mul_f32_e32 v116, v116, v159
	v_mul_f32_e32 v117, v117, v159
	v_mul_f32_e32 v118, 0xbfb8aa3b, v118
	v_mul_f32_e32 v119, 0xbfb8aa3b, v119
	v_mul_f32_e32 v120, 0xbfb8aa3b, v120
	v_mul_f32_e32 v121, 0xbfb8aa3b, v121
	v_mul_f32_e32 v114, 0xbfb8aa3b, v114
	v_mul_f32_e32 v115, 0xbfb8aa3b, v115
	v_mul_f32_e32 v116, 0xbfb8aa3b, v116
	v_mul_f32_e32 v117, 0xbfb8aa3b, v117
	v_exp_f32_e32 v118, v118
	v_exp_f32_e32 v119, v119
	v_exp_f32_e32 v120, v120
	v_exp_f32_e32 v121, v121
	v_exp_f32_e32 v114, v114
	v_exp_f32_e32 v115, v115
	v_exp_f32_e32 v116, v116
	v_exp_f32_e32 v117, v117
	v_add_f32_e32 v118, 1.0, v118
	v_add_f32_e32 v119, 1.0, v119
	v_add_f32_e32 v120, 1.0, v120
	v_add_f32_e32 v121, 1.0, v121
	v_add_f32_e32 v159, 1.0, v114
	v_add_f32_e32 v168, 1.0, v115
	v_add_f32_e32 v169, 1.0, v116
	v_add_f32_e32 v172, 1.0, v117
	v_rcp_f32_e32 v114, v118
	v_rcp_f32_e32 v115, v119
	v_rcp_f32_e32 v116, v120
	v_rcp_f32_e32 v117, v121
	v_rcp_f32_e32 v119, v168
	v_rcp_f32_e32 v120, v169
	v_rcp_f32_e32 v121, v172
	v_rcp_f32_e32 v118, v159
	v_pk_mul_f32 v[164:165], v[164:165], v[164:165]
	v_pk_mul_f32 v[166:167], v[166:167], v[166:167]
	v_pk_mul_f32 v[160:161], v[160:161], v[160:161]
	v_pk_mul_f32 v[162:163], v[162:163], v[162:163]
	s_ashr_i32 s55, s54, 31
	s_waitcnt vmcnt(5)
	v_lshlrev_b32_e32 v168, 16, v122
	v_and_b32_e32 v169, 0xffff0000, v122
	v_lshlrev_b32_e32 v122, 16, v123
	v_and_b32_e32 v123, 0xffff0000, v123
	s_waitcnt vmcnt(5)
	v_lshlrev_b32_e32 v172, 16, v126
	v_and_b32_e32 v173, 0xffff0000, v126
	v_lshlrev_b32_e32 v126, 16, v127
	v_and_b32_e32 v127, 0xffff0000, v127
	s_waitcnt vmcnt(5)
	v_lshlrev_b32_e32 v174, 16, v150
	v_and_b32_e32 v175, 0xffff0000, v150
	v_lshlrev_b32_e32 v150, 16, v151
	v_and_b32_e32 v151, 0xffff0000, v151
	v_pk_add_f32 v[168:169], v[172:173], v[168:169]
	v_pk_add_f32 v[122:123], v[126:127], v[122:123]
	v_pk_fma_f32 v[114:115], v[114:115], v[174:175], v[168:169]
	v_pk_fma_f32 v[122:123], v[116:117], v[150:151], v[122:123]
	v_cvt_pk_bf16_f32 v116, v114, v115
	v_cvt_pk_bf16_f32 v117, v122, v123
	v_lshlrev_b32_e32 v150, 16, v116
	v_and_b32_e32 v151, 0xffff0000, v116
	v_lshlrev_b32_e32 v168, 16, v117
	v_and_b32_e32 v169, 0xffff0000, v117
	v_pk_mul_f32 v[126:127], v[114:115], v[114:115]
	v_pk_add_f32 v[114:115], v[114:115], v[150:151] neg_lo:[0,1] neg_hi:[0,1]
	v_pk_mul_f32 v[150:151], v[122:123], v[122:123]
	v_pk_add_f32 v[122:123], v[122:123], v[168:169] neg_lo:[0,1] neg_hi:[0,1]
	v_lshlrev_b32_e32 v168, 16, v128
	v_and_b32_e32 v169, 0xffff0000, v128
	v_lshlrev_b32_e32 v172, 16, v124
	v_and_b32_e32 v173, 0xffff0000, v124
	v_pk_add_f32 v[168:169], v[168:169], v[172:173]
	v_lshlrev_b32_e32 v172, 16, v152
	v_and_b32_e32 v173, 0xffff0000, v152
	v_pk_fma_f32 v[168:169], v[118:119], v[172:173], v[168:169]
	v_add_f32_e32 v119, v164, v165
	v_add_f32_e32 v119, v166, v119
	v_add_f32_e32 v119, v167, v119
	v_add_f32_e32 v119, v160, v119
	v_add_f32_e32 v119, v161, v119
	v_add_f32_e32 v119, v162, v119
	v_add_f32_e32 v119, v163, v119
	v_add_f32_e32 v119, v126, v119
	v_add_f32_e32 v119, v127, v119
	v_lshlrev_b32_e32 v128, 16, v129
	v_and_b32_e32 v129, 0xffff0000, v129
	v_lshlrev_b32_e32 v124, 16, v125
	v_and_b32_e32 v125, 0xffff0000, v125
	v_add_f32_e32 v119, v150, v119
	v_pk_mul_f32 v[172:173], v[168:169], v[168:169]
	v_pk_add_f32 v[124:125], v[128:129], v[124:125]
	v_lshlrev_b32_e32 v128, 16, v153
	v_and_b32_e32 v129, 0xffff0000, v153
	v_add_f32_e32 v119, v151, v119
	v_pk_fma_f32 v[120:121], v[120:121], v[128:129], v[124:125]
	v_add_f32_e32 v119, v172, v119
	v_pk_mul_f32 v[124:125], v[120:121], v[120:121]
	v_add_f32_e32 v119, v173, v119
	v_add_f32_e32 v119, v124, v119
	v_add_f32_e32 v126, v125, v119
	v_mov_b32_e32 v127, v126
	s_nop 1
	v_permlane16_swap_b32_e32 v126, v127
	v_cvt_pk_bf16_f32 v119, v120, v121
	v_lshlrev_b32_e32 v124, 16, v119
	v_and_b32_e32 v125, 0xffff0000, v119
	v_pk_add_f32 v[124:125], v[120:121], v[124:125] neg_lo:[0,1] neg_hi:[0,1]
	v_cvt_pk_bf16_f32 v120, v114, v115
	s_waitcnt lgkmcnt(0)
	v_add_f32_e32 v114, v126, v127
	ds_bpermute_b32 v115, v145, v114
	v_cvt_pk_bf16_f32 v118, v168, v169
	v_lshlrev_b32_e32 v174, 16, v118
	v_and_b32_e32 v175, 0xffff0000, v118
	v_pk_add_f32 v[168:169], v[168:169], v[174:175] neg_lo:[0,1] neg_hi:[0,1]
	v_cvt_pk_bf16_f32 v121, v122, v123
	v_cvt_pk_bf16_f32 v123, v124, v125
	v_lshl_add_u64 v[124:125], s[58:59], 0, v[148:149]
	v_cvt_pk_bf16_f32 v122, v168, v169
	global_store_dwordx4 v[124:125], v[116:119], off
	global_store_dwordx4 v[170:171], v[120:123], off
	s_and_saveexec_b64 s[12:13], s[0:1]
	v_readlane_b32 s30, v251, 4
	v_readlane_b32 s31, v251, 5
	s_cbranch_execz .LBB0_1340
	v_readlane_b32 s44, v250, 8
	v_readlane_b32 s46, v250, 10
	v_readlane_b32 s47, v250, 11
	s_waitcnt lgkmcnt(0)
	v_add_f32_e32 v116, v114, v115
	s_lshl_b32 s40, s25, 2
	v_lshl_add_u64 v[114:115], s[46:47], 0, v[146:147]
	v_lshl_add_u64 v[114:115], s[54:55], 2, v[114:115]
	v_lshl_add_u64 v[114:115], v[114:115], 0, s[40:41]
	v_readlane_b32 s45, v250, 9
	global_store_dword v[114:115], v116, off
; __device__ __forceinline__ float row_ssq(const float* part, int pitch, int n4, int row, int fq) {
;     __device__ __forceinline__ void operator()(const f32x4 (&acc)[2][2][4][2], const Unit& u, int wr, int wc, int fr, int fq) const {
;     ...
;                 const int row = row0 + ai * HALF + m * 16;
;                 float rs = 0.f; if (GATED) rs = rsqrtf(row_ssq(ssq_in, 16, 4, row, fq) * (1.f / 1024.f) + EPS);
;                 float sq = 0.f;
; #pragma unroll
;                 for (int bj = 0; bj < 2; ++bj) {
;                     const size_t off = (size_t)row * DM + col0 + bj * HALF;
;                     const u32x4 hh = *(const u32x4*)(HI + off), ll = *(const u32x4*)(LO + off);
;                     float hv[8] = {bflo(hh.x) + bflo(ll.x), bfhi(hh.x) + bfhi(ll.x), bflo(hh.y) + bflo(ll.y), bfhi(hh.y) + bfhi(ll.y),
;                                    bflo(hh.z) + bflo(ll.z), bfhi(hh.z) + bfhi(ll.z), bflo(hh.w) + bflo(ll.w), bfhi(hh.w) + bfhi(ll.w)};
;                     float av[8] = {acc[ai][bj][m][0][0], acc[ai][bj][m][0][1], acc[ai][bj][m][0][2], acc[ai][bj][m][0][3], acc[ai][bj][m][1][0], acc[ai][bj][m][1][1], acc[ai][bj][m][1][2], acc[ai][bj][m][1][3]};
;                     if (GATED) { const u32x4 pp = *(const u32x4*)(PP + off);
;                         const float pv[8] = {bflo(pp.x), bfhi(pp.x), bflo(pp.y), bfhi(pp.y), bflo(pp.z), bfhi(pp.z), bflo(pp.w), bfhi(pp.w)};
; #pragma unroll
;                         for (int e = 0; e < 8; ++e) av[e] = fast_sigmoid(av[e] * rs) * pv[e]; }
;                     else {
; #pragma unroll
;                         for (int e = 0; e < 8; ++e) av[e] *= alpha; }
;                     float lo[8];
; #pragma unroll
;                     for (int e = 0; e < 8; ++e) { hv[e] += av[e]; sq += hv[e] * hv[e]; }
;                     u32x4 wh; wh.x = pk2(hv[0], hv[1]); wh.y = pk2(hv[2], hv[3]); wh.z = pk2(hv[4], hv[5]); wh.w = pk2(hv[6], hv[7]);
;                     lo[0] = hv[0] - bflo(wh.x); lo[1] = hv[1] - bfhi(wh.x); lo[2] = hv[2] - bflo(wh.y); lo[3] = hv[3] - bfhi(wh.y);
;                     lo[4] = hv[4] - bflo(wh.z); lo[5] = hv[5] - bfhi(wh.z); lo[6] = hv[6] - bflo(wh.w); lo[7] = hv[7] - bfhi(wh.w);
;                     u32x4 wl; wl.x = pk2(lo[0], lo[1]); wl.y = pk2(lo[2], lo[3]); wl.z = pk2(lo[4], lo[5]); wl.w = pk2(lo[6], lo[7]);
;                     *(u32x4*)(HO + off) = wh; *(u32x4*)(LO + off) = wl;
.LBB0_1340:
	s_or_b64 exec, exec, s[12:13]
	v_or_b32_e32 v120, 16, v144
	v_ashrrev_i32_e32 v121, 31, v120
	v_lshlrev_b64 v[118:119], 6, v[120:121]
	s_waitcnt lgkmcnt(0)
	v_lshl_add_u64 v[114:115], v[136:137], 0, v[118:119]
	global_load_dwordx4 v[114:117], v[114:115], off
	v_readlane_b32 s10, v253, 35
	v_readlane_b32 s11, v253, 36
	v_readlane_b32 s6, v250, 49
	v_readlane_b32 s7, v250, 50
	s_waitcnt vmcnt(0)
	v_mov_b32_e32 v122, v115
	v_mov_b32_e32 v123, v116
	v_mov_b32_e32 v115, v117
	v_pk_add_f32 v[114:115], v[122:123], v[114:115]
	s_nop 0
	v_add_f32_e32 v114, v114, v115
	v_mov_b32_e32 v115, v114
	s_nop 1
	v_permlane16_swap_b32_e32 v114, v115
	s_waitcnt lgkmcnt(0)
	v_add_f32_e32 v114, v114, v115
	v_mov_b32_e32 v115, v114
	s_nop 1
	v_permlane32_swap_b32_e32 v114, v115
	s_waitcnt lgkmcnt(0)
	v_add_f32_e32 v114, v114, v115
	v_fmamk_f32 v114, v114, 0x3a800000, v239
	v_cmp_gt_f32_e32 vcc, s16, v114
	v_mul_f32_e32 v115, 0x4b800000, v114
	s_nop 0
	v_cndmask_b32_e32 v114, v114, v115, vcc
	v_rsq_f32_e32 v114, v114
	s_nop 0
	v_mul_f32_e32 v115, 0x45800000, v114
	v_cndmask_b32_e32 v152, v114, v115, vcc
	v_lshlrev_b64 v[114:115], 10, v[120:121]
	v_lshl_add_u64 v[114:115], v[114:115], 0, v[142:143]
	v_lshlrev_b64 v[120:121], 1, v[114:115]
	v_lshl_add_u64 v[114:115], s[10:11], 0, v[120:121]
	v_lshl_add_u64 v[116:117], s[14:15], 0, v[120:121]
	global_load_dwordx4 v[126:129], v[114:115], off
	global_load_dwordx4 v[160:163], v[116:117], off
	v_lshl_add_u64 v[114:115], s[6:7], 0, v[120:121]
	global_load_dwordx4 v[146:149], v[114:115], off
	global_load_dwordx4 v[226:229], v120, s[10:11] offset:256
	global_load_dwordx4 v[234:237], v120, s[6:7] offset:256
	global_load_dwordx4 v[230:233], v120, s[14:15] offset:256
	v_mul_f32_e32 v106, v106, v152
	v_mul_f32_e32 v106, 0xbfb8aa3b, v106
	v_exp_f32_e32 v106, v106
	v_mul_f32_e32 v110, v110, v152
	v_mul_f32_e32 v111, v111, v152
	v_mul_f32_e32 v110, 0xbfb8aa3b, v110
	v_add_f32_e32 v106, 1.0, v106
	v_rcp_f32_e32 v116, v106
	v_mul_f32_e32 v106, v107, v152
	v_mul_f32_e32 v106, 0xbfb8aa3b, v106
	v_exp_f32_e32 v106, v106
	v_mul_f32_e32 v111, 0xbfb8aa3b, v111
	v_exp_f32_e32 v110, v110
	v_exp_f32_e32 v111, v111
	v_add_f32_e32 v106, 1.0, v106
	v_rcp_f32_e32 v117, v106
	v_mul_f32_e32 v106, v108, v152
	v_mul_f32_e32 v106, 0xbfb8aa3b, v106
	v_exp_f32_e32 v106, v106
	v_mul_f32_e32 v112, v112, v152
	v_mul_f32_e32 v113, v113, v152
	v_add_f32_e32 v110, 1.0, v110
	v_add_f32_e32 v106, 1.0, v106
	v_rcp_f32_e32 v150, v106
	v_mul_f32_e32 v106, v109, v152
	v_mul_f32_e32 v106, 0xbfb8aa3b, v106
	v_exp_f32_e32 v106, v106
	v_add_f32_e32 v111, 1.0, v111
	v_mul_f32_e32 v112, 0xbfb8aa3b, v112
	v_mul_f32_e32 v113, 0xbfb8aa3b, v113
	v_rcp_f32_e32 v110, v110
	v_rcp_f32_e32 v111, v111
	v_exp_f32_e32 v112, v112
	v_exp_f32_e32 v113, v113
	v_add_f32_e32 v106, 1.0, v106
	v_rcp_f32_e32 v151, v106
	v_add_f32_e32 v112, 1.0, v112
	v_add_f32_e32 v113, 1.0, v113
	v_rcp_f32_e32 v112, v112
	v_rcp_f32_e32 v113, v113
	v_mul_f32_e32 v102, v102, v152
	v_mul_f32_e32 v102, 0xbfb8aa3b, v102
	v_exp_f32_e32 v102, v102
	v_mul_f32_e32 v98, v98, v152
	v_mul_f32_e32 v98, 0xbfb8aa3b, v98
	v_exp_f32_e32 v98, v98
	v_add_f32_e32 v102, 1.0, v102
	v_add_f32_e32 v98, 1.0, v98
	s_waitcnt vmcnt(5)
	v_lshlrev_b32_e32 v106, 16, v126
	v_and_b32_e32 v107, 0xffff0000, v126
	s_waitcnt vmcnt(3)
	v_lshlrev_b32_e32 v108, 16, v146
	v_and_b32_e32 v109, 0xffff0000, v146
	v_pk_add_f32 v[106:107], v[106:107], v[108:109]
	v_lshlrev_b32_e32 v108, 16, v160
	v_and_b32_e32 v109, 0xffff0000, v160
	v_pk_fma_f32 v[108:109], v[110:111], v[108:109], v[106:107]
	v_lshlrev_b32_e32 v124, 16, v147
	v_cvt_pk_bf16_f32 v106, v108, v109
	v_lshlrev_b32_e32 v110, 16, v106
	v_and_b32_e32 v111, 0xffff0000, v106
	v_pk_mul_f32 v[122:123], v[108:109], v[108:109]
	v_pk_add_f32 v[110:111], v[108:109], v[110:111] neg_lo:[0,1] neg_hi:[0,1]
	v_lshlrev_b32_e32 v108, 16, v127
	v_and_b32_e32 v109, 0xffff0000, v127
	v_and_b32_e32 v125, 0xffff0000, v147
	v_pk_add_f32 v[108:109], v[108:109], v[124:125]
	v_lshlrev_b32_e32 v124, 16, v161
	v_and_b32_e32 v125, 0xffff0000, v161
	v_pk_fma_f32 v[108:109], v[112:113], v[124:125], v[108:109]
	v_lshlrev_b32_e32 v126, 16, v148
	v_cvt_pk_bf16_f32 v107, v108, v109
	v_lshlrev_b32_e32 v112, 16, v107
	v_and_b32_e32 v113, 0xffff0000, v107
	v_pk_mul_f32 v[124:125], v[108:109], v[108:109]
	v_pk_add_f32 v[112:113], v[108:109], v[112:113] neg_lo:[0,1] neg_hi:[0,1]
	v_lshlrev_b32_e32 v108, 16, v128
	v_and_b32_e32 v109, 0xffff0000, v128
	v_and_b32_e32 v127, 0xffff0000, v148
	v_pk_add_f32 v[108:109], v[108:109], v[126:127]
	v_lshlrev_b32_e32 v126, 16, v162
	v_and_b32_e32 v127, 0xffff0000, v162
	v_pk_fma_f32 v[116:117], v[116:117], v[126:127], v[108:109]
	v_lshlrev_b32_e32 v128, 16, v129
	v_cvt_pk_bf16_f32 v108, v116, v117
	v_lshlrev_b32_e32 v146, 16, v108
	v_and_b32_e32 v147, 0xffff0000, v108
	v_pk_mul_f32 v[126:127], v[116:117], v[116:117]
	v_pk_add_f32 v[116:117], v[116:117], v[146:147] neg_lo:[0,1] neg_hi:[0,1]
	v_and_b32_e32 v129, 0xffff0000, v129
	v_lshlrev_b32_e32 v146, 16, v149
	v_and_b32_e32 v147, 0xffff0000, v149
	v_pk_add_f32 v[128:129], v[128:129], v[146:147]
	v_lshlrev_b32_e32 v146, 16, v163
	v_and_b32_e32 v147, 0xffff0000, v163
	v_pk_fma_f32 v[146:147], v[150:151], v[146:147], v[128:129]
	v_cvt_pk_bf16_f32 v110, v110, v111
	v_cvt_pk_bf16_f32 v109, v146, v147
	v_lshlrev_b32_e32 v148, 16, v109
	v_and_b32_e32 v149, 0xffff0000, v109
	v_pk_mul_f32 v[128:129], v[146:147], v[146:147]
	v_pk_add_f32 v[146:147], v[146:147], v[148:149] neg_lo:[0,1] neg_hi:[0,1]
	v_cvt_pk_bf16_f32 v111, v112, v113
	v_cvt_pk_bf16_f32 v112, v116, v117
	v_lshl_add_u64 v[116:117], s[58:59], 0, v[120:121]
	v_or_b32_e32 v120, 0x100, v120
	v_cvt_pk_bf16_f32 v113, v146, v147
	global_store_dwordx4 v[116:117], v[106:109], off
	global_store_dwordx4 v[114:115], v[110:113], off
	v_lshl_add_u64 v[146:147], s[6:7], 0, v[120:121]
	v_lshl_add_u64 v[106:107], s[10:11], 0, v[120:121]
	s_waitcnt vmcnt(4)
; __device__ __forceinline__ float bflo(unsigned u) { return __uint_as_float(u << 16); }
;     __device__ __forceinline__ void operator()(const f32x4 (&acc)[2][2][4][2], const Unit& u, int wr, int wc, int fr, int fq) const {
;     ...
;                 for (int bj = 0; bj < 2; ++bj) {
;                     const size_t off = (size_t)row * DM + col0 + bj * HALF;
;                     const u32x4 hh = *(const u32x4*)(HI + off), ll = *(const u32x4*)(LO + off);
;                     float hv[8] = {bflo(hh.x) + bflo(ll.x), bfhi(hh.x) + bfhi(ll.x), bflo(hh.y) + bflo(ll.y), bfhi(hh.y) + bfhi(ll.y),
;                                    bflo(hh.z) + bflo(ll.z), bfhi(hh.z) + bfhi(ll.z), bflo(hh.w) + bflo(ll.w), bfhi(hh.w) + bfhi(ll.w)};
;                     float av[8] = {acc[ai][bj][m][0][0], acc[ai][bj][m][0][1], acc[ai][bj][m][0][2], acc[ai][bj][m][0][3], acc[ai][bj][m][1][0], acc[ai][bj][m][1][1], acc[ai][bj][m][1][2], acc[ai][bj][m][1][3]};
;                     if (GATED) { const u32x4 pp = *(const u32x4*)(PP + off);
;                         const float pv[8] = {bflo(pp.x), bfhi(pp.x), bflo(pp.y), bfhi(pp.y), bflo(pp.z), bfhi(pp.z), bflo(pp.w), bfhi(pp.w)};
; #pragma unroll
;                         for (int e = 0; e < 8; ++e) av[e] = fast_sigmoid(av[e] * rs) * pv[e]; }
;                     else {
; #pragma unroll
;                         for (int e = 0; e < 8; ++e) av[e] *= alpha; }
;                     float lo[8];
; #pragma unroll
;                     for (int e = 0; e < 8; ++e) { hv[e] += av[e]; sq += hv[e] * hv[e]; }
;                     u32x4 wh; wh.x = pk2(hv[0], hv[1]); wh.y = pk2(hv[2], hv[3]); wh.z = pk2(hv[4], hv[5]); wh.w = pk2(hv[6], hv[7]);
;                     lo[0] = hv[0] - bflo(wh.x); lo[1] = hv[1] - bfhi(wh.x); lo[2] = hv[2] - bflo(wh.y); lo[3] = hv[3] - bfhi(wh.y);
;                     lo[4] = hv[4] - bflo(wh.z); lo[5] = hv[5] - bfhi(wh.z); lo[6] = hv[6] - bflo(wh.w); lo[7] = hv[7] - bfhi(wh.w);
;                     u32x4 wl; wl.x = pk2(lo[0], lo[1]); wl.y = pk2(lo[2], lo[3]); wl.z = pk2(lo[4], lo[5]); wl.w = pk2(lo[6], lo[7]);
;                     *(u32x4*)(HO + off) = wh; *(u32x4*)(LO + off) = wl;
;                 }
;                 sq += __shfl_xor(sq, 16); sq += __shfl_xor(sq, 32);
;                 if (fq == 0) ssq_out[(size_t)row * 16 + 4 * u.pn + wc] = sq;
	s_nop 0
	v_mov_b32_e32 v106, v226
	v_mov_b32_e32 v107, v227
	v_mov_b32_e32 v108, v228
	v_mov_b32_e32 v109, v229
	v_lshl_add_u64 v[114:115], s[14:15], 0, v[120:121]
	s_waitcnt vmcnt(3)
	s_nop 0
	v_mov_b32_e32 v110, v234
	v_mov_b32_e32 v111, v235
	v_mov_b32_e32 v112, v236
	v_mov_b32_e32 v113, v237
	v_rcp_f32_e32 v150, v102
	s_waitcnt vmcnt(2)
	s_nop 0
	v_mov_b32_e32 v114, v230
	v_mov_b32_e32 v115, v231
	v_mov_b32_e32 v116, v232
	v_mov_b32_e32 v117, v233
	v_mul_f32_e32 v102, v103, v152
	v_mul_f32_e32 v102, 0xbfb8aa3b, v102
	v_exp_f32_e32 v102, v102
	s_nop 0
	v_add_f32_e32 v102, 1.0, v102
	v_rcp_f32_e32 v151, v102
	v_mul_f32_e32 v102, v104, v152
	v_rcp_f32_e32 v104, v98
	v_mul_f32_e32 v98, v99, v152
	v_mul_f32_e32 v102, 0xbfb8aa3b, v102
	v_mul_f32_e32 v98, 0xbfb8aa3b, v98
	v_exp_f32_e32 v102, v102
	v_exp_f32_e32 v98, v98
	v_add_f32_e32 v102, 1.0, v102
	v_add_f32_e32 v98, 1.0, v98
	v_rcp_f32_e32 v148, v102
	v_mul_f32_e32 v102, v105, v152
	v_rcp_f32_e32 v105, v98
	v_mul_f32_e32 v98, v100, v152
	v_mul_f32_e32 v102, 0xbfb8aa3b, v102
	v_mul_f32_e32 v98, 0xbfb8aa3b, v98
	v_exp_f32_e32 v102, v102
	v_exp_f32_e32 v98, v98
	v_add_f32_e32 v102, 1.0, v102
	v_add_f32_e32 v98, 1.0, v98
	v_rcp_f32_e32 v149, v102
	v_rcp_f32_e32 v102, v98
	v_mul_f32_e32 v98, v101, v152
	v_mul_f32_e32 v98, 0xbfb8aa3b, v98
	v_exp_f32_e32 v98, v98
	s_waitcnt vmcnt(5)
	v_and_b32_e32 v99, 0xffff0000, v106
	v_add_f32_e32 v98, 1.0, v98
	v_rcp_f32_e32 v103, v98
	v_lshlrev_b32_e32 v98, 16, v106
	s_waitcnt vmcnt(5)
	v_lshlrev_b32_e32 v100, 16, v110
	v_and_b32_e32 v101, 0xffff0000, v110
	v_pk_add_f32 v[98:99], v[98:99], v[100:101]
	s_waitcnt vmcnt(5)
	v_lshlrev_b32_e32 v100, 16, v114
	v_and_b32_e32 v101, 0xffff0000, v114
	v_pk_fma_f32 v[100:101], v[150:151], v[100:101], v[98:99]
	v_lshlrev_b32_e32 v106, 16, v111
	v_cvt_pk_bf16_f32 v98, v100, v101
	v_lshlrev_b32_e32 v150, 16, v98
	v_and_b32_e32 v151, 0xffff0000, v98
	v_pk_mul_f32 v[152:153], v[100:101], v[100:101]
	v_pk_add_f32 v[150:151], v[100:101], v[150:151] neg_lo:[0,1] neg_hi:[0,1]
	v_lshlrev_b32_e32 v100, 16, v107
	v_and_b32_e32 v101, 0xffff0000, v107
	v_and_b32_e32 v107, 0xffff0000, v111
	v_pk_add_f32 v[100:101], v[100:101], v[106:107]
	v_lshlrev_b32_e32 v106, 16, v115
	v_and_b32_e32 v107, 0xffff0000, v115
	v_pk_fma_f32 v[100:101], v[148:149], v[106:107], v[100:101]
	v_lshlrev_b32_e32 v114, 16, v112
	v_cvt_pk_bf16_f32 v99, v100, v101
	v_lshlrev_b32_e32 v110, 16, v99
	v_and_b32_e32 v111, 0xffff0000, v99
	v_pk_mul_f32 v[106:107], v[100:101], v[100:101]
	v_pk_add_f32 v[110:111], v[100:101], v[110:111] neg_lo:[0,1] neg_hi:[0,1]
	v_lshlrev_b32_e32 v100, 16, v108
	v_and_b32_e32 v101, 0xffff0000, v108
	v_and_b32_e32 v115, 0xffff0000, v112
	v_pk_add_f32 v[100:101], v[100:101], v[114:115]
	v_lshlrev_b32_e32 v114, 16, v116
	v_and_b32_e32 v115, 0xffff0000, v116
	v_pk_fma_f32 v[104:105], v[104:105], v[114:115], v[100:101]
	v_add_f32_e32 v101, v122, v123
	v_add_f32_e32 v101, v124, v101
	v_add_f32_e32 v101, v125, v101
	v_add_f32_e32 v101, v126, v101
	v_add_f32_e32 v101, v127, v101
	v_add_f32_e32 v101, v128, v101
	v_add_f32_e32 v101, v129, v101
	v_add_f32_e32 v101, v152, v101
	v_add_f32_e32 v101, v153, v101
	v_lshlrev_b32_e32 v108, 16, v109
	v_and_b32_e32 v109, 0xffff0000, v109
	v_lshlrev_b32_e32 v112, 16, v113
	v_and_b32_e32 v113, 0xffff0000, v113
	v_add_f32_e32 v101, v106, v101
	v_pk_mul_f32 v[114:115], v[104:105], v[104:105]
	v_pk_add_f32 v[108:109], v[108:109], v[112:113]
	v_lshlrev_b32_e32 v112, 16, v117
	v_and_b32_e32 v113, 0xffff0000, v117
	v_add_f32_e32 v101, v107, v101
	v_pk_fma_f32 v[102:103], v[102:103], v[112:113], v[108:109]
	v_add_f32_e32 v101, v114, v101
	v_pk_mul_f32 v[108:109], v[102:103], v[102:103]
	v_add_f32_e32 v101, v115, v101
	v_add_f32_e32 v101, v108, v101
	v_cvt_pk_bf16_f32 v100, v104, v105
	v_add_f32_e32 v108, v109, v101
	v_cvt_pk_bf16_f32 v101, v102, v103
	v_lshlrev_b32_e32 v148, 16, v100
	v_and_b32_e32 v149, 0xffff0000, v100
	v_lshlrev_b32_e32 v106, 16, v101
	v_and_b32_e32 v107, 0xffff0000, v101
	v_pk_add_f32 v[104:105], v[104:105], v[148:149] neg_lo:[0,1] neg_hi:[0,1]
	v_pk_add_f32 v[106:107], v[102:103], v[106:107] neg_lo:[0,1] neg_hi:[0,1]
	v_cvt_pk_bf16_f32 v104, v104, v105
	v_cvt_pk_bf16_f32 v105, v106, v107
	v_lshl_add_u64 v[106:107], s[58:59], 0, v[120:121]
	v_cvt_pk_bf16_f32 v102, v150, v151
	v_cvt_pk_bf16_f32 v103, v110, v111
	global_store_dwordx4 v[106:107], v[98:101], off
	global_store_dwordx4 v[146:147], v[102:105], off
	v_mov_b32_e32 v98, v108
	s_nop 1
	v_permlane16_swap_b32_e32 v108, v98
	s_waitcnt lgkmcnt(0)
	v_add_f32_e32 v98, v108, v98
	ds_bpermute_b32 v99, v145, v98
	s_and_saveexec_b64 s[12:13], s[0:1]
	s_cbranch_execz .LBB0_1342
	v_readlane_b32 s44, v250, 8
	v_readlane_b32 s46, v250, 10
	v_readlane_b32 s47, v250, 11
	s_waitcnt lgkmcnt(0)
	v_add_f32_e32 v100, v98, v99
	s_lshl_b32 s40, s25, 2
	v_lshl_add_u64 v[98:99], s[46:47], 0, v[118:119]
	v_lshl_add_u64 v[98:99], s[54:55], 2, v[98:99]
	v_lshl_add_u64 v[98:99], v[98:99], 0, s[40:41]
	v_readlane_b32 s45, v250, 9
	global_store_dword v[98:99], v100, off
; __device__ __forceinline__ float row_ssq(const float* part, int pitch, int n4, int row, int fq) {
;     __device__ __forceinline__ void operator()(const f32x4 (&acc)[2][2][4][2], const Unit& u, int wr, int wc, int fr, int fq) const {
;     ...
;                 const int row = row0 + ai * HALF + m * 16;
;                 float rs = 0.f; if (GATED) rs = rsqrtf(row_ssq(ssq_in, 16, 4, row, fq) * (1.f / 1024.f) + EPS);
;                 float sq = 0.f;
; #pragma unroll
;                 for (int bj = 0; bj < 2; ++bj) {
;                     const size_t off = (size_t)row * DM + col0 + bj * HALF;
;                     const u32x4 hh = *(const u32x4*)(HI + off), ll = *(const u32x4*)(LO + off);
;                     float hv[8] = {bflo(hh.x) + bflo(ll.x), bfhi(hh.x) + bfhi(ll.x), bflo(hh.y) + bflo(ll.y), bfhi(hh.y) + bfhi(ll.y),
;                                    bflo(hh.z) + bflo(ll.z), bfhi(hh.z) + bfhi(ll.z), bflo(hh.w) + bflo(ll.w), bfhi(hh.w) + bfhi(ll.w)};
;                     float av[8] = {acc[ai][bj][m][0][0], acc[ai][bj][m][0][1], acc[ai][bj][m][0][2], acc[ai][bj][m][0][3], acc[ai][bj][m][1][0], acc[ai][bj][m][1][1], acc[ai][bj][m][1][2], acc[ai][bj][m][1][3]};
;                     if (GATED) { const u32x4 pp = *(const u32x4*)(PP + off);
;                         const float pv[8] = {bflo(pp.x), bfhi(pp.x), bflo(pp.y), bfhi(pp.y), bflo(pp.z), bfhi(pp.z), bflo(pp.w), bfhi(pp.w)};
; #pragma unroll
;                         for (int e = 0; e < 8; ++e) av[e] = fast_sigmoid(av[e] * rs) * pv[e]; }
;                     else {
; #pragma unroll
;                         for (int e = 0; e < 8; ++e) av[e] *= alpha; }
;                     float lo[8];
; #pragma unroll
;                     for (int e = 0; e < 8; ++e) { hv[e] += av[e]; sq += hv[e] * hv[e]; }
;                     u32x4 wh; wh.x = pk2(hv[0], hv[1]); wh.y = pk2(hv[2], hv[3]); wh.z = pk2(hv[4], hv[5]); wh.w = pk2(hv[6], hv[7]);
;                     lo[0] = hv[0] - bflo(wh.x); lo[1] = hv[1] - bfhi(wh.x); lo[2] = hv[2] - bflo(wh.y); lo[3] = hv[3] - bfhi(wh.y);
;                     lo[4] = hv[4] - bflo(wh.z); lo[5] = hv[5] - bfhi(wh.z); lo[6] = hv[6] - bflo(wh.w); lo[7] = hv[7] - bfhi(wh.w);
;                     u32x4 wl; wl.x = pk2(lo[0], lo[1]); wl.y = pk2(lo[2], lo[3]); wl.z = pk2(lo[4], lo[5]); wl.w = pk2(lo[6], lo[7]);
;                     *(u32x4*)(HO + off) = wh; *(u32x4*)(LO + off) = wl;
.LBB0_1342:
	s_or_b64 exec, exec, s[12:13]
	v_or_b32_e32 v104, 32, v144
	v_ashrrev_i32_e32 v105, 31, v104
	v_lshlrev_b64 v[102:103], 6, v[104:105]
	s_waitcnt lgkmcnt(0)
	v_lshl_add_u64 v[98:99], v[136:137], 0, v[102:103]
	global_load_dwordx4 v[98:101], v[98:99], off
	v_readlane_b32 s10, v253, 35
	v_readlane_b32 s11, v253, 36
	v_readlane_b32 s6, v250, 49
	v_readlane_b32 s7, v250, 50
	s_waitcnt vmcnt(0)
	v_mov_b32_e32 v106, v99
	v_mov_b32_e32 v107, v100
	v_mov_b32_e32 v99, v101
	v_pk_add_f32 v[98:99], v[106:107], v[98:99]
	s_nop 0
	v_add_f32_e32 v98, v98, v99
	v_mov_b32_e32 v99, v98
	s_nop 1
	v_permlane16_swap_b32_e32 v98, v99
	s_waitcnt lgkmcnt(0)
	v_add_f32_e32 v98, v98, v99
	v_mov_b32_e32 v99, v98
	s_nop 1
	v_permlane32_swap_b32_e32 v98, v99
	s_waitcnt lgkmcnt(0)
	v_add_f32_e32 v98, v98, v99
	v_fmamk_f32 v98, v98, 0x3a800000, v239
	v_cmp_gt_f32_e32 vcc, s16, v98
	v_mul_f32_e32 v99, 0x4b800000, v98
	s_nop 0
	v_cndmask_b32_e32 v98, v98, v99, vcc
	v_rsq_f32_e32 v98, v98
	s_nop 0
	v_mul_f32_e32 v99, 0x45800000, v98
	v_cndmask_b32_e32 v120, v98, v99, vcc
	v_lshlrev_b64 v[98:99], 10, v[104:105]
	v_lshl_add_u64 v[98:99], v[98:99], 0, v[142:143]
	v_lshlrev_b64 v[104:105], 1, v[98:99]
	v_lshl_add_u64 v[98:99], s[10:11], 0, v[104:105]
	v_lshl_add_u64 v[100:101], s[14:15], 0, v[104:105]
	global_load_dwordx4 v[110:113], v[98:99], off
	global_load_dwordx4 v[122:125], v[100:101], off
	v_lshl_add_u64 v[98:99], s[6:7], 0, v[104:105]
	global_load_dwordx4 v[114:117], v[98:99], off
	global_load_dwordx4 v[226:229], v104, s[10:11] offset:256
	global_load_dwordx4 v[234:237], v104, s[6:7] offset:256
	global_load_dwordx4 v[230:233], v104, s[14:15] offset:256
	v_mul_f32_e32 v90, v90, v120
	v_mul_f32_e32 v90, 0xbfb8aa3b, v90
	v_exp_f32_e32 v90, v90
	v_mul_f32_e32 v94, v94, v120
	v_mul_f32_e32 v95, v95, v120
	v_mul_f32_e32 v94, 0xbfb8aa3b, v94
	v_add_f32_e32 v90, 1.0, v90
	v_rcp_f32_e32 v100, v90
	v_mul_f32_e32 v90, v91, v120
	v_mul_f32_e32 v90, 0xbfb8aa3b, v90
	v_exp_f32_e32 v90, v90
	v_mul_f32_e32 v95, 0xbfb8aa3b, v95
	v_exp_f32_e32 v94, v94
	v_exp_f32_e32 v95, v95
	v_add_f32_e32 v90, 1.0, v90
	v_rcp_f32_e32 v101, v90
	v_mul_f32_e32 v90, v92, v120
	v_mul_f32_e32 v90, 0xbfb8aa3b, v90
	v_exp_f32_e32 v90, v90
	v_mul_f32_e32 v96, v96, v120
	v_mul_f32_e32 v97, v97, v120
	v_add_f32_e32 v94, 1.0, v94
	v_add_f32_e32 v90, 1.0, v90
	v_rcp_f32_e32 v118, v90
	v_mul_f32_e32 v90, v93, v120
	v_mul_f32_e32 v90, 0xbfb8aa3b, v90
	v_exp_f32_e32 v90, v90
	v_add_f32_e32 v95, 1.0, v95
	v_mul_f32_e32 v96, 0xbfb8aa3b, v96
	v_mul_f32_e32 v97, 0xbfb8aa3b, v97
	v_rcp_f32_e32 v94, v94
	v_rcp_f32_e32 v95, v95
	v_exp_f32_e32 v96, v96
	v_exp_f32_e32 v97, v97
	v_add_f32_e32 v90, 1.0, v90
	v_rcp_f32_e32 v119, v90
	v_add_f32_e32 v96, 1.0, v96
	v_add_f32_e32 v97, 1.0, v97
	v_rcp_f32_e32 v96, v96
	v_rcp_f32_e32 v97, v97
	v_mul_f32_e32 v86, v86, v120
	v_mul_f32_e32 v86, 0xbfb8aa3b, v86
	v_exp_f32_e32 v86, v86
	v_mul_f32_e32 v82, v82, v120
	v_mul_f32_e32 v82, 0xbfb8aa3b, v82
	v_exp_f32_e32 v82, v82
	v_add_f32_e32 v86, 1.0, v86
	v_add_f32_e32 v82, 1.0, v82
	s_waitcnt vmcnt(5)
	v_lshlrev_b32_e32 v90, 16, v110
	v_and_b32_e32 v91, 0xffff0000, v110
	s_waitcnt vmcnt(3)
	v_lshlrev_b32_e32 v92, 16, v114
	v_and_b32_e32 v93, 0xffff0000, v114
	v_pk_add_f32 v[90:91], v[90:91], v[92:93]
	v_lshlrev_b32_e32 v92, 16, v122
	v_and_b32_e32 v93, 0xffff0000, v122
	v_pk_fma_f32 v[92:93], v[94:95], v[92:93], v[90:91]
	v_lshlrev_b32_e32 v108, 16, v115
	v_cvt_pk_bf16_f32 v90, v92, v93
	v_lshlrev_b32_e32 v94, 16, v90
	v_and_b32_e32 v95, 0xffff0000, v90
	v_pk_mul_f32 v[106:107], v[92:93], v[92:93]
	v_pk_add_f32 v[94:95], v[92:93], v[94:95] neg_lo:[0,1] neg_hi:[0,1]
	v_lshlrev_b32_e32 v92, 16, v111
	v_and_b32_e32 v93, 0xffff0000, v111
	v_and_b32_e32 v109, 0xffff0000, v115
	v_pk_add_f32 v[92:93], v[92:93], v[108:109]
	v_lshlrev_b32_e32 v108, 16, v123
	v_and_b32_e32 v109, 0xffff0000, v123
	v_pk_fma_f32 v[92:93], v[96:97], v[108:109], v[92:93]
	v_lshlrev_b32_e32 v110, 16, v116
	v_cvt_pk_bf16_f32 v91, v92, v93
	v_lshlrev_b32_e32 v96, 16, v91
	v_and_b32_e32 v97, 0xffff0000, v91
	v_pk_mul_f32 v[108:109], v[92:93], v[92:93]
	v_pk_add_f32 v[96:97], v[92:93], v[96:97] neg_lo:[0,1] neg_hi:[0,1]
	v_lshlrev_b32_e32 v92, 16, v112
	v_and_b32_e32 v93, 0xffff0000, v112
	v_and_b32_e32 v111, 0xffff0000, v116
	v_pk_add_f32 v[92:93], v[92:93], v[110:111]
	v_lshlrev_b32_e32 v110, 16, v124
	v_and_b32_e32 v111, 0xffff0000, v124
	v_pk_fma_f32 v[100:101], v[100:101], v[110:111], v[92:93]
	v_lshlrev_b32_e32 v112, 16, v113
	v_cvt_pk_bf16_f32 v92, v100, v101
	v_lshlrev_b32_e32 v114, 16, v92
	v_and_b32_e32 v115, 0xffff0000, v92
	v_pk_mul_f32 v[110:111], v[100:101], v[100:101]
	v_pk_add_f32 v[100:101], v[100:101], v[114:115] neg_lo:[0,1] neg_hi:[0,1]
	v_and_b32_e32 v113, 0xffff0000, v113
	v_lshlrev_b32_e32 v114, 16, v117
	v_and_b32_e32 v115, 0xffff0000, v117
	v_pk_add_f32 v[112:113], v[112:113], v[114:115]
	v_lshlrev_b32_e32 v114, 16, v125
	v_and_b32_e32 v115, 0xffff0000, v125
	v_pk_fma_f32 v[114:115], v[118:119], v[114:115], v[112:113]
	v_cvt_pk_bf16_f32 v94, v94, v95
	v_cvt_pk_bf16_f32 v93, v114, v115
	v_lshlrev_b32_e32 v116, 16, v93
	v_and_b32_e32 v117, 0xffff0000, v93
	v_pk_mul_f32 v[112:113], v[114:115], v[114:115]
	v_pk_add_f32 v[114:115], v[114:115], v[116:117] neg_lo:[0,1] neg_hi:[0,1]
	v_cvt_pk_bf16_f32 v95, v96, v97
	v_cvt_pk_bf16_f32 v96, v100, v101
	v_lshl_add_u64 v[100:101], s[58:59], 0, v[104:105]
	v_or_b32_e32 v104, 0x100, v104
	v_cvt_pk_bf16_f32 v97, v114, v115
	global_store_dwordx4 v[100:101], v[90:93], off
	global_store_dwordx4 v[98:99], v[94:97], off
	v_lshl_add_u64 v[114:115], s[6:7], 0, v[104:105]
	v_lshl_add_u64 v[90:91], s[10:11], 0, v[104:105]
	s_waitcnt vmcnt(4)
; __device__ __forceinline__ float bflo(unsigned u) { return __uint_as_float(u << 16); }
;     __device__ __forceinline__ void operator()(const f32x4 (&acc)[2][2][4][2], const Unit& u, int wr, int wc, int fr, int fq) const {
;     ...
;                 for (int bj = 0; bj < 2; ++bj) {
;                     const size_t off = (size_t)row * DM + col0 + bj * HALF;
;                     const u32x4 hh = *(const u32x4*)(HI + off), ll = *(const u32x4*)(LO + off);
;                     float hv[8] = {bflo(hh.x) + bflo(ll.x), bfhi(hh.x) + bfhi(ll.x), bflo(hh.y) + bflo(ll.y), bfhi(hh.y) + bfhi(ll.y),
;                                    bflo(hh.z) + bflo(ll.z), bfhi(hh.z) + bfhi(ll.z), bflo(hh.w) + bflo(ll.w), bfhi(hh.w) + bfhi(ll.w)};
;                     float av[8] = {acc[ai][bj][m][0][0], acc[ai][bj][m][0][1], acc[ai][bj][m][0][2], acc[ai][bj][m][0][3], acc[ai][bj][m][1][0], acc[ai][bj][m][1][1], acc[ai][bj][m][1][2], acc[ai][bj][m][1][3]};
;                     if (GATED) { const u32x4 pp = *(const u32x4*)(PP + off);
;                         const float pv[8] = {bflo(pp.x), bfhi(pp.x), bflo(pp.y), bfhi(pp.y), bflo(pp.z), bfhi(pp.z), bflo(pp.w), bfhi(pp.w)};
; #pragma unroll
;                         for (int e = 0; e < 8; ++e) av[e] = fast_sigmoid(av[e] * rs) * pv[e]; }
;                     else {
; #pragma unroll
;                         for (int e = 0; e < 8; ++e) av[e] *= alpha; }
;                     float lo[8];
; #pragma unroll
;                     for (int e = 0; e < 8; ++e) { hv[e] += av[e]; sq += hv[e] * hv[e]; }
;                     u32x4 wh; wh.x = pk2(hv[0], hv[1]); wh.y = pk2(hv[2], hv[3]); wh.z = pk2(hv[4], hv[5]); wh.w = pk2(hv[6], hv[7]);
;                     lo[0] = hv[0] - bflo(wh.x); lo[1] = hv[1] - bfhi(wh.x); lo[2] = hv[2] - bflo(wh.y); lo[3] = hv[3] - bfhi(wh.y);
;                     lo[4] = hv[4] - bflo(wh.z); lo[5] = hv[5] - bfhi(wh.z); lo[6] = hv[6] - bflo(wh.w); lo[7] = hv[7] - bfhi(wh.w);
;                     u32x4 wl; wl.x = pk2(lo[0], lo[1]); wl.y = pk2(lo[2], lo[3]); wl.z = pk2(lo[4], lo[5]); wl.w = pk2(lo[6], lo[7]);
;                     *(u32x4*)(HO + off) = wh; *(u32x4*)(LO + off) = wl;
;                 }
;                 sq += __shfl_xor(sq, 16); sq += __shfl_xor(sq, 32);
;                 if (fq == 0) ssq_out[(size_t)row * 16 + 4 * u.pn + wc] = sq;
	s_nop 0
	v_mov_b32_e32 v90, v226
	v_mov_b32_e32 v91, v227
	v_mov_b32_e32 v92, v228
	v_mov_b32_e32 v93, v229
	v_lshl_add_u64 v[98:99], s[14:15], 0, v[104:105]
	s_waitcnt vmcnt(3)
	s_nop 0
	v_mov_b32_e32 v94, v234
	v_mov_b32_e32 v95, v235
	v_mov_b32_e32 v96, v236
	v_mov_b32_e32 v97, v237
	v_rcp_f32_e32 v118, v86
	s_waitcnt vmcnt(2)
	s_nop 0
	v_mov_b32_e32 v98, v230
	v_mov_b32_e32 v99, v231
	v_mov_b32_e32 v100, v232
	v_mov_b32_e32 v101, v233
	v_mul_f32_e32 v86, v87, v120
	v_mul_f32_e32 v86, 0xbfb8aa3b, v86
	v_exp_f32_e32 v86, v86
	s_nop 0
	v_add_f32_e32 v86, 1.0, v86
	v_rcp_f32_e32 v119, v86
	v_mul_f32_e32 v86, v88, v120
	v_rcp_f32_e32 v88, v82
	v_mul_f32_e32 v82, v83, v120
	v_mul_f32_e32 v86, 0xbfb8aa3b, v86
	v_mul_f32_e32 v82, 0xbfb8aa3b, v82
	v_exp_f32_e32 v86, v86
	v_exp_f32_e32 v82, v82
	v_add_f32_e32 v86, 1.0, v86
	v_add_f32_e32 v82, 1.0, v82
	v_rcp_f32_e32 v116, v86
	v_mul_f32_e32 v86, v89, v120
	v_rcp_f32_e32 v89, v82
	v_mul_f32_e32 v82, v84, v120
	v_mul_f32_e32 v86, 0xbfb8aa3b, v86
	v_mul_f32_e32 v82, 0xbfb8aa3b, v82
	v_exp_f32_e32 v86, v86
	v_exp_f32_e32 v82, v82
	v_add_f32_e32 v86, 1.0, v86
	v_add_f32_e32 v82, 1.0, v82
	v_rcp_f32_e32 v117, v86
	v_rcp_f32_e32 v86, v82
	v_mul_f32_e32 v82, v85, v120
	v_mul_f32_e32 v82, 0xbfb8aa3b, v82
	v_exp_f32_e32 v82, v82
	s_waitcnt vmcnt(5)
	v_and_b32_e32 v83, 0xffff0000, v90
	v_add_f32_e32 v82, 1.0, v82
	v_rcp_f32_e32 v87, v82
	v_lshlrev_b32_e32 v82, 16, v90
	s_waitcnt vmcnt(5)
	v_lshlrev_b32_e32 v84, 16, v94
	v_and_b32_e32 v85, 0xffff0000, v94
	v_pk_add_f32 v[82:83], v[82:83], v[84:85]
	s_waitcnt vmcnt(5)
	v_lshlrev_b32_e32 v84, 16, v98
	v_and_b32_e32 v85, 0xffff0000, v98
	v_pk_fma_f32 v[84:85], v[118:119], v[84:85], v[82:83]
	v_lshlrev_b32_e32 v90, 16, v95
	v_cvt_pk_bf16_f32 v82, v84, v85
	v_lshlrev_b32_e32 v118, 16, v82
	v_and_b32_e32 v119, 0xffff0000, v82
	v_pk_mul_f32 v[120:121], v[84:85], v[84:85]
	v_pk_add_f32 v[118:119], v[84:85], v[118:119] neg_lo:[0,1] neg_hi:[0,1]
	v_lshlrev_b32_e32 v84, 16, v91
	v_and_b32_e32 v85, 0xffff0000, v91
	v_and_b32_e32 v91, 0xffff0000, v95
	v_pk_add_f32 v[84:85], v[84:85], v[90:91]
	v_lshlrev_b32_e32 v90, 16, v99
	v_and_b32_e32 v91, 0xffff0000, v99
	v_pk_fma_f32 v[84:85], v[116:117], v[90:91], v[84:85]
	v_lshlrev_b32_e32 v98, 16, v96
	v_cvt_pk_bf16_f32 v83, v84, v85
	v_lshlrev_b32_e32 v94, 16, v83
	v_and_b32_e32 v95, 0xffff0000, v83
	v_pk_mul_f32 v[90:91], v[84:85], v[84:85]
	v_pk_add_f32 v[94:95], v[84:85], v[94:95] neg_lo:[0,1] neg_hi:[0,1]
	v_lshlrev_b32_e32 v84, 16, v92
	v_and_b32_e32 v85, 0xffff0000, v92
	v_and_b32_e32 v99, 0xffff0000, v96
	v_pk_add_f32 v[84:85], v[84:85], v[98:99]
	v_lshlrev_b32_e32 v98, 16, v100
	v_and_b32_e32 v99, 0xffff0000, v100
	v_pk_fma_f32 v[88:89], v[88:89], v[98:99], v[84:85]
	v_add_f32_e32 v85, v106, v107
	v_add_f32_e32 v85, v108, v85
	v_add_f32_e32 v85, v109, v85
	v_add_f32_e32 v85, v110, v85
	v_add_f32_e32 v85, v111, v85
	v_add_f32_e32 v85, v112, v85
	v_add_f32_e32 v85, v113, v85
	v_add_f32_e32 v85, v120, v85
	v_add_f32_e32 v85, v121, v85
	v_lshlrev_b32_e32 v92, 16, v93
	v_and_b32_e32 v93, 0xffff0000, v93
	v_lshlrev_b32_e32 v96, 16, v97
	v_and_b32_e32 v97, 0xffff0000, v97
	v_add_f32_e32 v85, v90, v85
	v_pk_mul_f32 v[98:99], v[88:89], v[88:89]
	v_pk_add_f32 v[92:93], v[92:93], v[96:97]
	v_lshlrev_b32_e32 v96, 16, v101
	v_and_b32_e32 v97, 0xffff0000, v101
	v_add_f32_e32 v85, v91, v85
	v_pk_fma_f32 v[86:87], v[86:87], v[96:97], v[92:93]
	v_add_f32_e32 v85, v98, v85
	v_pk_mul_f32 v[92:93], v[86:87], v[86:87]
	v_add_f32_e32 v85, v99, v85
	v_add_f32_e32 v85, v92, v85
	v_cvt_pk_bf16_f32 v84, v88, v89
	v_add_f32_e32 v92, v93, v85
	v_cvt_pk_bf16_f32 v85, v86, v87
	v_lshlrev_b32_e32 v116, 16, v84
	v_and_b32_e32 v117, 0xffff0000, v84
	v_lshlrev_b32_e32 v90, 16, v85
	v_and_b32_e32 v91, 0xffff0000, v85
	v_pk_add_f32 v[88:89], v[88:89], v[116:117] neg_lo:[0,1] neg_hi:[0,1]
	v_pk_add_f32 v[90:91], v[86:87], v[90:91] neg_lo:[0,1] neg_hi:[0,1]
	v_cvt_pk_bf16_f32 v88, v88, v89
	v_cvt_pk_bf16_f32 v89, v90, v91
	v_lshl_add_u64 v[90:91], s[58:59], 0, v[104:105]
	v_cvt_pk_bf16_f32 v86, v118, v119
	v_cvt_pk_bf16_f32 v87, v94, v95
	global_store_dwordx4 v[90:91], v[82:85], off
	global_store_dwordx4 v[114:115], v[86:89], off
	v_mov_b32_e32 v82, v92
	s_nop 1
	v_permlane16_swap_b32_e32 v92, v82
	s_waitcnt lgkmcnt(0)
	v_add_f32_e32 v82, v92, v82
	ds_bpermute_b32 v83, v145, v82
	s_and_saveexec_b64 s[12:13], s[0:1]
	s_cbranch_execz .LBB0_1344
	v_readlane_b32 s44, v250, 8
	v_readlane_b32 s46, v250, 10
	v_readlane_b32 s47, v250, 11
	s_waitcnt lgkmcnt(0)
	v_add_f32_e32 v84, v82, v83
	s_lshl_b32 s40, s25, 2
	v_lshl_add_u64 v[82:83], s[46:47], 0, v[102:103]
	v_lshl_add_u64 v[82:83], s[54:55], 2, v[82:83]
	v_lshl_add_u64 v[82:83], v[82:83], 0, s[40:41]
	v_readlane_b32 s45, v250, 9
	global_store_dword v[82:83], v84, off
; __device__ __forceinline__ float row_ssq(const float* part, int pitch, int n4, int row, int fq) {
;     __device__ __forceinline__ void operator()(const f32x4 (&acc)[2][2][4][2], const Unit& u, int wr, int wc, int fr, int fq) const {
;     ...
;                 const int row = row0 + ai * HALF + m * 16;
;                 float rs = 0.f; if (GATED) rs = rsqrtf(row_ssq(ssq_in, 16, 4, row, fq) * (1.f / 1024.f) + EPS);
;                 float sq = 0.f;
; #pragma unroll
;                 for (int bj = 0; bj < 2; ++bj) {
;                     const size_t off = (size_t)row * DM + col0 + bj * HALF;
;                     const u32x4 hh = *(const u32x4*)(HI + off), ll = *(const u32x4*)(LO + off);
;                     float hv[8] = {bflo(hh.x) + bflo(ll.x), bfhi(hh.x) + bfhi(ll.x), bflo(hh.y) + bflo(ll.y), bfhi(hh.y) + bfhi(ll.y),
;                                    bflo(hh.z) + bflo(ll.z), bfhi(hh.z) + bfhi(ll.z), bflo(hh.w) + bflo(ll.w), bfhi(hh.w) + bfhi(ll.w)};
;                     float av[8] = {acc[ai][bj][m][0][0], acc[ai][bj][m][0][1], acc[ai][bj][m][0][2], acc[ai][bj][m][0][3], acc[ai][bj][m][1][0], acc[ai][bj][m][1][1], acc[ai][bj][m][1][2], acc[ai][bj][m][1][3]};
;                     if (GATED) { const u32x4 pp = *(const u32x4*)(PP + off);
;                         const float pv[8] = {bflo(pp.x), bfhi(pp.x), bflo(pp.y), bfhi(pp.y), bflo(pp.z), bfhi(pp.z), bflo(pp.w), bfhi(pp.w)};
; #pragma unroll
;                         for (int e = 0; e < 8; ++e) av[e] = fast_sigmoid(av[e] * rs) * pv[e]; }
;                     else {
; #pragma unroll
;                         for (int e = 0; e < 8; ++e) av[e] *= alpha; }
;                     float lo[8];
; #pragma unroll
;                     for (int e = 0; e < 8; ++e) { hv[e] += av[e]; sq += hv[e] * hv[e]; }
;                     u32x4 wh; wh.x = pk2(hv[0], hv[1]); wh.y = pk2(hv[2], hv[3]); wh.z = pk2(hv[4], hv[5]); wh.w = pk2(hv[6], hv[7]);
;                     lo[0] = hv[0] - bflo(wh.x); lo[1] = hv[1] - bfhi(wh.x); lo[2] = hv[2] - bflo(wh.y); lo[3] = hv[3] - bfhi(wh.y);
;                     lo[4] = hv[4] - bflo(wh.z); lo[5] = hv[5] - bfhi(wh.z); lo[6] = hv[6] - bflo(wh.w); lo[7] = hv[7] - bfhi(wh.w);
;                     u32x4 wl; wl.x = pk2(lo[0], lo[1]); wl.y = pk2(lo[2], lo[3]); wl.z = pk2(lo[4], lo[5]); wl.w = pk2(lo[6], lo[7]);
;                     *(u32x4*)(HO + off) = wh; *(u32x4*)(LO + off) = wl;
.LBB0_1344:
	s_or_b64 exec, exec, s[12:13]
	v_or_b32_e32 v88, 48, v144
	v_ashrrev_i32_e32 v89, 31, v88
	v_lshlrev_b64 v[86:87], 6, v[88:89]
	s_waitcnt lgkmcnt(0)
	v_lshl_add_u64 v[82:83], v[136:137], 0, v[86:87]
	global_load_dwordx4 v[82:85], v[82:83], off
	v_readlane_b32 s10, v253, 35
	v_readlane_b32 s11, v253, 36
	v_readlane_b32 s6, v250, 49
	v_readlane_b32 s7, v250, 50
	s_waitcnt vmcnt(0)
	v_mov_b32_e32 v90, v83
	v_mov_b32_e32 v91, v84
	v_mov_b32_e32 v83, v85
	v_pk_add_f32 v[82:83], v[90:91], v[82:83]
	s_nop 0
	v_add_f32_e32 v82, v82, v83
	v_mov_b32_e32 v83, v82
	s_nop 1
	v_permlane16_swap_b32_e32 v82, v83
	s_waitcnt lgkmcnt(0)
	v_add_f32_e32 v82, v82, v83
	v_mov_b32_e32 v83, v82
	s_nop 1
	v_permlane32_swap_b32_e32 v82, v83
	s_waitcnt lgkmcnt(0)
	v_add_f32_e32 v82, v82, v83
	v_fmamk_f32 v82, v82, 0x3a800000, v239
	v_cmp_gt_f32_e32 vcc, s16, v82
	v_mul_f32_e32 v83, 0x4b800000, v82
	s_nop 0
	v_cndmask_b32_e32 v82, v82, v83, vcc
	v_rsq_f32_e32 v82, v82
	s_nop 0
	v_mul_f32_e32 v83, 0x45800000, v82
	v_cndmask_b32_e32 v104, v82, v83, vcc
	v_lshlrev_b64 v[82:83], 10, v[88:89]
	v_lshl_add_u64 v[82:83], v[82:83], 0, v[142:143]
	v_lshlrev_b64 v[88:89], 1, v[82:83]
	v_lshl_add_u64 v[82:83], s[10:11], 0, v[88:89]
	v_lshl_add_u64 v[84:85], s[14:15], 0, v[88:89]
	global_load_dwordx4 v[94:97], v[82:83], off
	global_load_dwordx4 v[106:109], v[84:85], off
	v_lshl_add_u64 v[82:83], s[6:7], 0, v[88:89]
	global_load_dwordx4 v[98:101], v[82:83], off
	global_load_dwordx4 v[226:229], v88, s[10:11] offset:256
	global_load_dwordx4 v[234:237], v88, s[6:7] offset:256
	global_load_dwordx4 v[230:233], v88, s[14:15] offset:256
	v_mul_f32_e32 v74, v74, v104
	v_mul_f32_e32 v74, 0xbfb8aa3b, v74
	v_exp_f32_e32 v74, v74
	v_mul_f32_e32 v78, v78, v104
	v_mul_f32_e32 v79, v79, v104
	v_mul_f32_e32 v78, 0xbfb8aa3b, v78
	v_add_f32_e32 v74, 1.0, v74
	v_rcp_f32_e32 v84, v74
	v_mul_f32_e32 v74, v75, v104
	v_mul_f32_e32 v74, 0xbfb8aa3b, v74
	v_exp_f32_e32 v74, v74
	v_mul_f32_e32 v79, 0xbfb8aa3b, v79
	v_exp_f32_e32 v78, v78
	v_exp_f32_e32 v79, v79
	v_add_f32_e32 v74, 1.0, v74
	v_rcp_f32_e32 v85, v74
	v_mul_f32_e32 v74, v76, v104
	v_mul_f32_e32 v74, 0xbfb8aa3b, v74
	v_exp_f32_e32 v74, v74
	v_mul_f32_e32 v80, v80, v104
	v_mul_f32_e32 v81, v81, v104
	v_add_f32_e32 v78, 1.0, v78
	v_add_f32_e32 v74, 1.0, v74
	v_rcp_f32_e32 v102, v74
	v_mul_f32_e32 v74, v77, v104
	v_mul_f32_e32 v74, 0xbfb8aa3b, v74
	v_exp_f32_e32 v74, v74
	v_add_f32_e32 v79, 1.0, v79
	v_mul_f32_e32 v80, 0xbfb8aa3b, v80
	v_mul_f32_e32 v81, 0xbfb8aa3b, v81
	v_rcp_f32_e32 v78, v78
	v_rcp_f32_e32 v79, v79
	v_exp_f32_e32 v80, v80
	v_exp_f32_e32 v81, v81
	v_add_f32_e32 v74, 1.0, v74
	v_rcp_f32_e32 v103, v74
	v_add_f32_e32 v80, 1.0, v80
	v_add_f32_e32 v81, 1.0, v81
	v_rcp_f32_e32 v80, v80
	v_rcp_f32_e32 v81, v81
	v_mul_f32_e32 v70, v70, v104
	v_mul_f32_e32 v70, 0xbfb8aa3b, v70
	v_exp_f32_e32 v70, v70
	v_mul_f32_e32 v66, v66, v104
	v_mul_f32_e32 v66, 0xbfb8aa3b, v66
	v_exp_f32_e32 v66, v66
	v_add_f32_e32 v70, 1.0, v70
	v_add_f32_e32 v66, 1.0, v66
	s_waitcnt vmcnt(5)
	v_lshlrev_b32_e32 v74, 16, v94
	v_and_b32_e32 v75, 0xffff0000, v94
	s_waitcnt vmcnt(3)
	v_lshlrev_b32_e32 v76, 16, v98
	v_and_b32_e32 v77, 0xffff0000, v98
	v_pk_add_f32 v[74:75], v[74:75], v[76:77]
	v_lshlrev_b32_e32 v76, 16, v106
	v_and_b32_e32 v77, 0xffff0000, v106
	v_pk_fma_f32 v[76:77], v[78:79], v[76:77], v[74:75]
	v_lshlrev_b32_e32 v92, 16, v99
	v_cvt_pk_bf16_f32 v74, v76, v77
	v_lshlrev_b32_e32 v78, 16, v74
	v_and_b32_e32 v79, 0xffff0000, v74
	v_pk_mul_f32 v[90:91], v[76:77], v[76:77]
	v_pk_add_f32 v[78:79], v[76:77], v[78:79] neg_lo:[0,1] neg_hi:[0,1]
	v_lshlrev_b32_e32 v76, 16, v95
	v_and_b32_e32 v77, 0xffff0000, v95
	v_and_b32_e32 v93, 0xffff0000, v99
	v_pk_add_f32 v[76:77], v[76:77], v[92:93]
	v_lshlrev_b32_e32 v92, 16, v107
	v_and_b32_e32 v93, 0xffff0000, v107
	v_pk_fma_f32 v[76:77], v[80:81], v[92:93], v[76:77]
	v_lshlrev_b32_e32 v94, 16, v100
	v_cvt_pk_bf16_f32 v75, v76, v77
	v_lshlrev_b32_e32 v80, 16, v75
	v_and_b32_e32 v81, 0xffff0000, v75
	v_pk_mul_f32 v[92:93], v[76:77], v[76:77]
	v_pk_add_f32 v[80:81], v[76:77], v[80:81] neg_lo:[0,1] neg_hi:[0,1]
	v_lshlrev_b32_e32 v76, 16, v96
	v_and_b32_e32 v77, 0xffff0000, v96
	v_and_b32_e32 v95, 0xffff0000, v100
	v_pk_add_f32 v[76:77], v[76:77], v[94:95]
	v_lshlrev_b32_e32 v94, 16, v108
	v_and_b32_e32 v95, 0xffff0000, v108
	v_pk_fma_f32 v[84:85], v[84:85], v[94:95], v[76:77]
	v_lshlrev_b32_e32 v96, 16, v97
	v_cvt_pk_bf16_f32 v76, v84, v85
	v_lshlrev_b32_e32 v98, 16, v76
	v_and_b32_e32 v99, 0xffff0000, v76
	v_pk_mul_f32 v[94:95], v[84:85], v[84:85]
	v_pk_add_f32 v[84:85], v[84:85], v[98:99] neg_lo:[0,1] neg_hi:[0,1]
	v_and_b32_e32 v97, 0xffff0000, v97
	v_lshlrev_b32_e32 v98, 16, v101
	v_and_b32_e32 v99, 0xffff0000, v101
	v_pk_add_f32 v[96:97], v[96:97], v[98:99]
	v_lshlrev_b32_e32 v98, 16, v109
	v_and_b32_e32 v99, 0xffff0000, v109
	v_pk_fma_f32 v[98:99], v[102:103], v[98:99], v[96:97]
	v_cvt_pk_bf16_f32 v78, v78, v79
	v_cvt_pk_bf16_f32 v77, v98, v99
	v_lshlrev_b32_e32 v100, 16, v77
	v_and_b32_e32 v101, 0xffff0000, v77
	v_pk_mul_f32 v[96:97], v[98:99], v[98:99]
	v_pk_add_f32 v[98:99], v[98:99], v[100:101] neg_lo:[0,1] neg_hi:[0,1]
	v_cvt_pk_bf16_f32 v79, v80, v81
	v_cvt_pk_bf16_f32 v80, v84, v85
	v_lshl_add_u64 v[84:85], s[58:59], 0, v[88:89]
	v_or_b32_e32 v88, 0x100, v88
	v_cvt_pk_bf16_f32 v81, v98, v99
	global_store_dwordx4 v[84:85], v[74:77], off
	global_store_dwordx4 v[82:83], v[78:81], off
	v_lshl_add_u64 v[98:99], s[6:7], 0, v[88:89]
	v_lshl_add_u64 v[74:75], s[10:11], 0, v[88:89]
	s_waitcnt vmcnt(4)
	s_nop 0
	v_mov_b32_e32 v74, v226
	v_mov_b32_e32 v75, v227
	v_mov_b32_e32 v76, v228
	v_mov_b32_e32 v77, v229
	v_lshl_add_u64 v[82:83], s[14:15], 0, v[88:89]
	s_waitcnt vmcnt(3)
; __device__ __forceinline__ float bflo(unsigned u) { return __uint_as_float(u << 16); }
;     __device__ __forceinline__ void operator()(const f32x4 (&acc)[2][2][4][2], const Unit& u, int wr, int wc, int fr, int fq) const {
;     ...
;                 for (int bj = 0; bj < 2; ++bj) {
;                     const size_t off = (size_t)row * DM + col0 + bj * HALF;
;                     const u32x4 hh = *(const u32x4*)(HI + off), ll = *(const u32x4*)(LO + off);
;                     float hv[8] = {bflo(hh.x) + bflo(ll.x), bfhi(hh.x) + bfhi(ll.x), bflo(hh.y) + bflo(ll.y), bfhi(hh.y) + bfhi(ll.y),
;                                    bflo(hh.z) + bflo(ll.z), bfhi(hh.z) + bfhi(ll.z), bflo(hh.w) + bflo(ll.w), bfhi(hh.w) + bfhi(ll.w)};
;                     float av[8] = {acc[ai][bj][m][0][0], acc[ai][bj][m][0][1], acc[ai][bj][m][0][2], acc[ai][bj][m][0][3], acc[ai][bj][m][1][0], acc[ai][bj][m][1][1], acc[ai][bj][m][1][2], acc[ai][bj][m][1][3]};
;                     if (GATED) { const u32x4 pp = *(const u32x4*)(PP + off);
;                         const float pv[8] = {bflo(pp.x), bfhi(pp.x), bflo(pp.y), bfhi(pp.y), bflo(pp.z), bfhi(pp.z), bflo(pp.w), bfhi(pp.w)};
; #pragma unroll
;                         for (int e = 0; e < 8; ++e) av[e] = fast_sigmoid(av[e] * rs) * pv[e]; }
;                     else {
; #pragma unroll
;                         for (int e = 0; e < 8; ++e) av[e] *= alpha; }
;                     float lo[8];
; #pragma unroll
;                     for (int e = 0; e < 8; ++e) { hv[e] += av[e]; sq += hv[e] * hv[e]; }
;                     u32x4 wh; wh.x = pk2(hv[0], hv[1]); wh.y = pk2(hv[2], hv[3]); wh.z = pk2(hv[4], hv[5]); wh.w = pk2(hv[6], hv[7]);
;                     lo[0] = hv[0] - bflo(wh.x); lo[1] = hv[1] - bfhi(wh.x); lo[2] = hv[2] - bflo(wh.y); lo[3] = hv[3] - bfhi(wh.y);
;                     lo[4] = hv[4] - bflo(wh.z); lo[5] = hv[5] - bfhi(wh.z); lo[6] = hv[6] - bflo(wh.w); lo[7] = hv[7] - bfhi(wh.w);
;                     u32x4 wl; wl.x = pk2(lo[0], lo[1]); wl.y = pk2(lo[2], lo[3]); wl.z = pk2(lo[4], lo[5]); wl.w = pk2(lo[6], lo[7]);
;                     *(u32x4*)(HO + off) = wh; *(u32x4*)(LO + off) = wl;
;                 }
;                 sq += __shfl_xor(sq, 16); sq += __shfl_xor(sq, 32);
;                 if (fq == 0) ssq_out[(size_t)row * 16 + 4 * u.pn + wc] = sq;
	s_nop 0
	v_mov_b32_e32 v78, v234
	v_mov_b32_e32 v79, v235
	v_mov_b32_e32 v80, v236
	v_mov_b32_e32 v81, v237
	v_rcp_f32_e32 v102, v70
	s_waitcnt vmcnt(2)
	s_nop 0
	v_mov_b32_e32 v82, v230
	v_mov_b32_e32 v83, v231
	v_mov_b32_e32 v84, v232
	v_mov_b32_e32 v85, v233
	v_mul_f32_e32 v70, v71, v104
	v_mul_f32_e32 v70, 0xbfb8aa3b, v70
	v_exp_f32_e32 v70, v70
	s_nop 0
	v_add_f32_e32 v70, 1.0, v70
	v_rcp_f32_e32 v103, v70
	v_mul_f32_e32 v70, v72, v104
	v_rcp_f32_e32 v72, v66
	v_mul_f32_e32 v66, v67, v104
	v_mul_f32_e32 v70, 0xbfb8aa3b, v70
	v_mul_f32_e32 v66, 0xbfb8aa3b, v66
	v_exp_f32_e32 v70, v70
	v_exp_f32_e32 v66, v66
	v_add_f32_e32 v70, 1.0, v70
	v_add_f32_e32 v66, 1.0, v66
	v_rcp_f32_e32 v100, v70
	v_mul_f32_e32 v70, v73, v104
	v_rcp_f32_e32 v73, v66
	v_mul_f32_e32 v66, v68, v104
	v_mul_f32_e32 v70, 0xbfb8aa3b, v70
	v_mul_f32_e32 v66, 0xbfb8aa3b, v66
	v_exp_f32_e32 v70, v70
	v_exp_f32_e32 v66, v66
	v_add_f32_e32 v70, 1.0, v70
	v_add_f32_e32 v66, 1.0, v66
	v_rcp_f32_e32 v101, v70
	v_rcp_f32_e32 v70, v66
	v_mul_f32_e32 v66, v69, v104
	v_mul_f32_e32 v66, 0xbfb8aa3b, v66
	v_exp_f32_e32 v66, v66
	s_waitcnt vmcnt(5)
	v_and_b32_e32 v67, 0xffff0000, v74
	v_add_f32_e32 v66, 1.0, v66
	v_rcp_f32_e32 v71, v66
	v_lshlrev_b32_e32 v66, 16, v74
	s_waitcnt vmcnt(5)
	v_lshlrev_b32_e32 v68, 16, v78
	v_and_b32_e32 v69, 0xffff0000, v78
	v_pk_add_f32 v[66:67], v[66:67], v[68:69]
	s_waitcnt vmcnt(5)
	v_lshlrev_b32_e32 v68, 16, v82
	v_and_b32_e32 v69, 0xffff0000, v82
	v_pk_fma_f32 v[68:69], v[102:103], v[68:69], v[66:67]
	v_lshlrev_b32_e32 v74, 16, v79
	v_cvt_pk_bf16_f32 v66, v68, v69
	v_lshlrev_b32_e32 v102, 16, v66
	v_and_b32_e32 v103, 0xffff0000, v66
	v_pk_mul_f32 v[104:105], v[68:69], v[68:69]
	v_pk_add_f32 v[102:103], v[68:69], v[102:103] neg_lo:[0,1] neg_hi:[0,1]
	v_lshlrev_b32_e32 v68, 16, v75
	v_and_b32_e32 v69, 0xffff0000, v75
	v_and_b32_e32 v75, 0xffff0000, v79
	v_pk_add_f32 v[68:69], v[68:69], v[74:75]
	v_lshlrev_b32_e32 v74, 16, v83
	v_and_b32_e32 v75, 0xffff0000, v83
	v_pk_fma_f32 v[68:69], v[100:101], v[74:75], v[68:69]
	v_lshlrev_b32_e32 v82, 16, v80
	v_cvt_pk_bf16_f32 v67, v68, v69
	v_lshlrev_b32_e32 v78, 16, v67
	v_and_b32_e32 v79, 0xffff0000, v67
	v_pk_mul_f32 v[74:75], v[68:69], v[68:69]
	v_pk_add_f32 v[78:79], v[68:69], v[78:79] neg_lo:[0,1] neg_hi:[0,1]
	v_lshlrev_b32_e32 v68, 16, v76
	v_and_b32_e32 v69, 0xffff0000, v76
	v_and_b32_e32 v83, 0xffff0000, v80
	v_pk_add_f32 v[68:69], v[68:69], v[82:83]
	v_lshlrev_b32_e32 v82, 16, v84
	v_and_b32_e32 v83, 0xffff0000, v84
	v_pk_fma_f32 v[72:73], v[72:73], v[82:83], v[68:69]
	v_add_f32_e32 v69, v90, v91
	v_add_f32_e32 v69, v92, v69
	v_add_f32_e32 v69, v93, v69
	v_add_f32_e32 v69, v94, v69
	v_add_f32_e32 v69, v95, v69
	v_add_f32_e32 v69, v96, v69
	v_add_f32_e32 v69, v97, v69
	v_add_f32_e32 v69, v104, v69
	v_add_f32_e32 v69, v105, v69
	v_lshlrev_b32_e32 v76, 16, v77
	v_and_b32_e32 v77, 0xffff0000, v77
	v_lshlrev_b32_e32 v80, 16, v81
	v_and_b32_e32 v81, 0xffff0000, v81
	v_add_f32_e32 v69, v74, v69
	v_pk_mul_f32 v[82:83], v[72:73], v[72:73]
	v_pk_add_f32 v[76:77], v[76:77], v[80:81]
	v_lshlrev_b32_e32 v80, 16, v85
	v_and_b32_e32 v81, 0xffff0000, v85
	v_add_f32_e32 v69, v75, v69
	v_pk_fma_f32 v[70:71], v[70:71], v[80:81], v[76:77]
	v_add_f32_e32 v69, v82, v69
	v_pk_mul_f32 v[76:77], v[70:71], v[70:71]
	v_add_f32_e32 v69, v83, v69
	v_add_f32_e32 v69, v76, v69
	v_cvt_pk_bf16_f32 v68, v72, v73
	v_add_f32_e32 v76, v77, v69
	v_cvt_pk_bf16_f32 v69, v70, v71
	v_lshlrev_b32_e32 v100, 16, v68
	v_and_b32_e32 v101, 0xffff0000, v68
	v_lshlrev_b32_e32 v74, 16, v69
	v_and_b32_e32 v75, 0xffff0000, v69
	v_pk_add_f32 v[72:73], v[72:73], v[100:101] neg_lo:[0,1] neg_hi:[0,1]
	v_pk_add_f32 v[74:75], v[70:71], v[74:75] neg_lo:[0,1] neg_hi:[0,1]
	v_cvt_pk_bf16_f32 v72, v72, v73
	v_cvt_pk_bf16_f32 v73, v74, v75
	v_lshl_add_u64 v[74:75], s[58:59], 0, v[88:89]
	v_cvt_pk_bf16_f32 v70, v102, v103
	v_cvt_pk_bf16_f32 v71, v78, v79
	global_store_dwordx4 v[74:75], v[66:69], off
	global_store_dwordx4 v[98:99], v[70:73], off
	v_mov_b32_e32 v66, v76
	s_nop 1
	v_permlane16_swap_b32_e32 v76, v66
	s_waitcnt lgkmcnt(0)
	v_add_f32_e32 v66, v76, v66
	ds_bpermute_b32 v67, v145, v66
	s_and_saveexec_b64 s[12:13], s[0:1]
	s_cbranch_execz .LBB0_1346
	v_readlane_b32 s44, v250, 8
	v_readlane_b32 s46, v250, 10
	v_readlane_b32 s47, v250, 11
	s_waitcnt lgkmcnt(0)
	v_add_f32_e32 v68, v66, v67
	s_lshl_b32 s40, s25, 2
	v_lshl_add_u64 v[66:67], s[46:47], 0, v[86:87]
	v_lshl_add_u64 v[66:67], s[54:55], 2, v[66:67]
	v_lshl_add_u64 v[66:67], v[66:67], 0, s[40:41]
	v_readlane_b32 s45, v250, 9
	global_store_dword v[66:67], v68, off
; __device__ __forceinline__ float row_ssq(const float* part, int pitch, int n4, int row, int fq) {
;     __device__ __forceinline__ void operator()(const f32x4 (&acc)[2][2][4][2], const Unit& u, int wr, int wc, int fr, int fq) const {
;     ...
;                 const int row = row0 + ai * HALF + m * 16;
;                 float rs = 0.f; if (GATED) rs = rsqrtf(row_ssq(ssq_in, 16, 4, row, fq) * (1.f / 1024.f) + EPS);
;                 float sq = 0.f;
; #pragma unroll
;                 for (int bj = 0; bj < 2; ++bj) {
;                     const size_t off = (size_t)row * DM + col0 + bj * HALF;
;                     const u32x4 hh = *(const u32x4*)(HI + off), ll = *(const u32x4*)(LO + off);
;                     float hv[8] = {bflo(hh.x) + bflo(ll.x), bfhi(hh.x) + bfhi(ll.x), bflo(hh.y) + bflo(ll.y), bfhi(hh.y) + bfhi(ll.y),
;                                    bflo(hh.z) + bflo(ll.z), bfhi(hh.z) + bfhi(ll.z), bflo(hh.w) + bflo(ll.w), bfhi(hh.w) + bfhi(ll.w)};
;                     float av[8] = {acc[ai][bj][m][0][0], acc[ai][bj][m][0][1], acc[ai][bj][m][0][2], acc[ai][bj][m][0][3], acc[ai][bj][m][1][0], acc[ai][bj][m][1][1], acc[ai][bj][m][1][2], acc[ai][bj][m][1][3]};
;                     if (GATED) { const u32x4 pp = *(const u32x4*)(PP + off);
;                         const float pv[8] = {bflo(pp.x), bfhi(pp.x), bflo(pp.y), bfhi(pp.y), bflo(pp.z), bfhi(pp.z), bflo(pp.w), bfhi(pp.w)};
; #pragma unroll
;                         for (int e = 0; e < 8; ++e) av[e] = fast_sigmoid(av[e] * rs) * pv[e]; }
;                     else {
; #pragma unroll
;                         for (int e = 0; e < 8; ++e) av[e] *= alpha; }
;                     float lo[8];
; #pragma unroll
;                     for (int e = 0; e < 8; ++e) { hv[e] += av[e]; sq += hv[e] * hv[e]; }
;                     u32x4 wh; wh.x = pk2(hv[0], hv[1]); wh.y = pk2(hv[2], hv[3]); wh.z = pk2(hv[4], hv[5]); wh.w = pk2(hv[6], hv[7]);
;                     lo[0] = hv[0] - bflo(wh.x); lo[1] = hv[1] - bfhi(wh.x); lo[2] = hv[2] - bflo(wh.y); lo[3] = hv[3] - bfhi(wh.y);
;                     lo[4] = hv[4] - bflo(wh.z); lo[5] = hv[5] - bfhi(wh.z); lo[6] = hv[6] - bflo(wh.w); lo[7] = hv[7] - bfhi(wh.w);
;                     u32x4 wl; wl.x = pk2(lo[0], lo[1]); wl.y = pk2(lo[2], lo[3]); wl.z = pk2(lo[4], lo[5]); wl.w = pk2(lo[6], lo[7]);
;                     *(u32x4*)(HO + off) = wh; *(u32x4*)(LO + off) = wl;
.LBB0_1346:
	s_or_b64 exec, exec, s[12:13]
	v_add_u32_e32 v72, 0x80, v144
	v_ashrrev_i32_e32 v73, 31, v72
	v_lshlrev_b64 v[70:71], 6, v[72:73]
	s_waitcnt lgkmcnt(0)
	v_lshl_add_u64 v[66:67], v[136:137], 0, v[70:71]
	global_load_dwordx4 v[66:69], v[66:67], off
	v_readlane_b32 s10, v253, 35
	v_readlane_b32 s11, v253, 36
	v_readlane_b32 s6, v250, 49
	v_readlane_b32 s7, v250, 50
	s_waitcnt vmcnt(0)
	v_mov_b32_e32 v74, v67
	v_mov_b32_e32 v75, v68
	v_mov_b32_e32 v67, v69
	v_pk_add_f32 v[66:67], v[74:75], v[66:67]
	s_nop 0
	v_add_f32_e32 v66, v66, v67
	v_mov_b32_e32 v67, v66
	s_nop 1
	v_permlane16_swap_b32_e32 v66, v67
	s_waitcnt lgkmcnt(0)
	v_add_f32_e32 v66, v66, v67
	v_mov_b32_e32 v67, v66
	s_nop 1
	v_permlane32_swap_b32_e32 v66, v67
	s_waitcnt lgkmcnt(0)
	v_add_f32_e32 v66, v66, v67
	v_fmamk_f32 v66, v66, 0x3a800000, v239
	v_cmp_gt_f32_e32 vcc, s16, v66
	v_mul_f32_e32 v67, 0x4b800000, v66
	s_nop 0
	v_cndmask_b32_e32 v66, v66, v67, vcc
	v_rsq_f32_e32 v66, v66
	s_nop 0
	v_mul_f32_e32 v67, 0x45800000, v66
	v_cndmask_b32_e32 v88, v66, v67, vcc
	v_lshlrev_b64 v[66:67], 10, v[72:73]
	v_lshl_add_u64 v[66:67], v[66:67], 0, v[142:143]
	v_lshlrev_b64 v[72:73], 1, v[66:67]
	v_lshl_add_u64 v[66:67], s[10:11], 0, v[72:73]
	v_lshl_add_u64 v[68:69], s[14:15], 0, v[72:73]
	global_load_dwordx4 v[78:81], v[66:67], off
	global_load_dwordx4 v[90:93], v[68:69], off
	v_lshl_add_u64 v[66:67], s[6:7], 0, v[72:73]
	global_load_dwordx4 v[82:85], v[66:67], off
	global_load_dwordx4 v[226:229], v72, s[10:11] offset:256
	global_load_dwordx4 v[234:237], v72, s[6:7] offset:256
	global_load_dwordx4 v[230:233], v72, s[14:15] offset:256
	v_mul_f32_e32 v58, v58, v88
	v_mul_f32_e32 v58, 0xbfb8aa3b, v58
	v_exp_f32_e32 v58, v58
	v_mul_f32_e32 v62, v62, v88
	v_mul_f32_e32 v63, v63, v88
	v_mul_f32_e32 v62, 0xbfb8aa3b, v62
	v_add_f32_e32 v58, 1.0, v58
	v_rcp_f32_e32 v68, v58
	v_mul_f32_e32 v58, v59, v88
	v_mul_f32_e32 v58, 0xbfb8aa3b, v58
	v_exp_f32_e32 v58, v58
	v_mul_f32_e32 v63, 0xbfb8aa3b, v63
	v_exp_f32_e32 v62, v62
	v_exp_f32_e32 v63, v63
	v_add_f32_e32 v58, 1.0, v58
	v_rcp_f32_e32 v69, v58
	v_mul_f32_e32 v58, v60, v88
	v_mul_f32_e32 v58, 0xbfb8aa3b, v58
	v_exp_f32_e32 v58, v58
	v_mul_f32_e32 v64, v64, v88
	v_mul_f32_e32 v65, v65, v88
	v_add_f32_e32 v62, 1.0, v62
	v_add_f32_e32 v58, 1.0, v58
	v_rcp_f32_e32 v86, v58
	v_mul_f32_e32 v58, v61, v88
	v_mul_f32_e32 v58, 0xbfb8aa3b, v58
	v_exp_f32_e32 v58, v58
	v_add_f32_e32 v63, 1.0, v63
	v_mul_f32_e32 v64, 0xbfb8aa3b, v64
	v_mul_f32_e32 v65, 0xbfb8aa3b, v65
	v_rcp_f32_e32 v62, v62
	v_rcp_f32_e32 v63, v63
	v_exp_f32_e32 v64, v64
	v_exp_f32_e32 v65, v65
	v_add_f32_e32 v58, 1.0, v58
	v_rcp_f32_e32 v87, v58
	v_add_f32_e32 v64, 1.0, v64
	v_add_f32_e32 v65, 1.0, v65
	v_rcp_f32_e32 v64, v64
	v_rcp_f32_e32 v65, v65
	v_mul_f32_e32 v54, v54, v88
	v_mul_f32_e32 v54, 0xbfb8aa3b, v54
	v_exp_f32_e32 v54, v54
	v_mul_f32_e32 v50, v50, v88
	v_mul_f32_e32 v50, 0xbfb8aa3b, v50
	v_exp_f32_e32 v50, v50
	v_add_f32_e32 v54, 1.0, v54
	v_add_f32_e32 v50, 1.0, v50
	s_waitcnt vmcnt(5)
	v_lshlrev_b32_e32 v58, 16, v78
	v_and_b32_e32 v59, 0xffff0000, v78
	s_waitcnt vmcnt(3)
	v_lshlrev_b32_e32 v60, 16, v82
	v_and_b32_e32 v61, 0xffff0000, v82
	v_pk_add_f32 v[58:59], v[58:59], v[60:61]
	v_lshlrev_b32_e32 v60, 16, v90
	v_and_b32_e32 v61, 0xffff0000, v90
	v_pk_fma_f32 v[60:61], v[62:63], v[60:61], v[58:59]
	v_lshlrev_b32_e32 v76, 16, v83
	v_cvt_pk_bf16_f32 v58, v60, v61
	v_lshlrev_b32_e32 v62, 16, v58
	v_and_b32_e32 v63, 0xffff0000, v58
	v_pk_mul_f32 v[74:75], v[60:61], v[60:61]
	v_pk_add_f32 v[62:63], v[60:61], v[62:63] neg_lo:[0,1] neg_hi:[0,1]
	v_lshlrev_b32_e32 v60, 16, v79
	v_and_b32_e32 v61, 0xffff0000, v79
	v_and_b32_e32 v77, 0xffff0000, v83
	v_pk_add_f32 v[60:61], v[60:61], v[76:77]
	v_lshlrev_b32_e32 v76, 16, v91
	v_and_b32_e32 v77, 0xffff0000, v91
	v_pk_fma_f32 v[60:61], v[64:65], v[76:77], v[60:61]
	v_lshlrev_b32_e32 v78, 16, v84
	v_cvt_pk_bf16_f32 v59, v60, v61
	v_lshlrev_b32_e32 v64, 16, v59
	v_and_b32_e32 v65, 0xffff0000, v59
	v_pk_mul_f32 v[76:77], v[60:61], v[60:61]
	v_pk_add_f32 v[64:65], v[60:61], v[64:65] neg_lo:[0,1] neg_hi:[0,1]
	v_lshlrev_b32_e32 v60, 16, v80
	v_and_b32_e32 v61, 0xffff0000, v80
	v_and_b32_e32 v79, 0xffff0000, v84
	v_pk_add_f32 v[60:61], v[60:61], v[78:79]
	v_lshlrev_b32_e32 v78, 16, v92
	v_and_b32_e32 v79, 0xffff0000, v92
	v_pk_fma_f32 v[68:69], v[68:69], v[78:79], v[60:61]
	v_lshlrev_b32_e32 v80, 16, v81
	v_cvt_pk_bf16_f32 v60, v68, v69
	v_lshlrev_b32_e32 v82, 16, v60
	v_and_b32_e32 v83, 0xffff0000, v60
	v_pk_mul_f32 v[78:79], v[68:69], v[68:69]
	v_pk_add_f32 v[68:69], v[68:69], v[82:83] neg_lo:[0,1] neg_hi:[0,1]
	v_and_b32_e32 v81, 0xffff0000, v81
	v_lshlrev_b32_e32 v82, 16, v85
	v_and_b32_e32 v83, 0xffff0000, v85
	v_pk_add_f32 v[80:81], v[80:81], v[82:83]
	v_lshlrev_b32_e32 v82, 16, v93
	v_and_b32_e32 v83, 0xffff0000, v93
	v_pk_fma_f32 v[82:83], v[86:87], v[82:83], v[80:81]
	v_cvt_pk_bf16_f32 v62, v62, v63
	v_cvt_pk_bf16_f32 v61, v82, v83
	v_lshlrev_b32_e32 v84, 16, v61
	v_and_b32_e32 v85, 0xffff0000, v61
	v_pk_mul_f32 v[80:81], v[82:83], v[82:83]
	v_pk_add_f32 v[82:83], v[82:83], v[84:85] neg_lo:[0,1] neg_hi:[0,1]
	v_cvt_pk_bf16_f32 v63, v64, v65
	v_cvt_pk_bf16_f32 v64, v68, v69
	v_lshl_add_u64 v[68:69], s[58:59], 0, v[72:73]
	v_or_b32_e32 v72, 0x100, v72
	v_cvt_pk_bf16_f32 v65, v82, v83
	global_store_dwordx4 v[68:69], v[58:61], off
	global_store_dwordx4 v[66:67], v[62:65], off
	v_lshl_add_u64 v[82:83], s[6:7], 0, v[72:73]
	v_lshl_add_u64 v[58:59], s[10:11], 0, v[72:73]
	s_waitcnt vmcnt(4)
	s_nop 0
	v_mov_b32_e32 v58, v226
	v_mov_b32_e32 v59, v227
	v_mov_b32_e32 v60, v228
	v_mov_b32_e32 v61, v229
	v_lshl_add_u64 v[66:67], s[14:15], 0, v[72:73]
	s_waitcnt vmcnt(3)
; __device__ __forceinline__ float bflo(unsigned u) { return __uint_as_float(u << 16); }
;     __device__ __forceinline__ void operator()(const f32x4 (&acc)[2][2][4][2], const Unit& u, int wr, int wc, int fr, int fq) const {
;     ...
;                 for (int bj = 0; bj < 2; ++bj) {
;                     const size_t off = (size_t)row * DM + col0 + bj * HALF;
;                     const u32x4 hh = *(const u32x4*)(HI + off), ll = *(const u32x4*)(LO + off);
;                     float hv[8] = {bflo(hh.x) + bflo(ll.x), bfhi(hh.x) + bfhi(ll.x), bflo(hh.y) + bflo(ll.y), bfhi(hh.y) + bfhi(ll.y),
;                                    bflo(hh.z) + bflo(ll.z), bfhi(hh.z) + bfhi(ll.z), bflo(hh.w) + bflo(ll.w), bfhi(hh.w) + bfhi(ll.w)};
;                     float av[8] = {acc[ai][bj][m][0][0], acc[ai][bj][m][0][1], acc[ai][bj][m][0][2], acc[ai][bj][m][0][3], acc[ai][bj][m][1][0], acc[ai][bj][m][1][1], acc[ai][bj][m][1][2], acc[ai][bj][m][1][3]};
;                     if (GATED) { const u32x4 pp = *(const u32x4*)(PP + off);
;                         const float pv[8] = {bflo(pp.x), bfhi(pp.x), bflo(pp.y), bfhi(pp.y), bflo(pp.z), bfhi(pp.z), bflo(pp.w), bfhi(pp.w)};
; #pragma unroll
;                         for (int e = 0; e < 8; ++e) av[e] = fast_sigmoid(av[e] * rs) * pv[e]; }
;                     else {
; #pragma unroll
;                         for (int e = 0; e < 8; ++e) av[e] *= alpha; }
;                     float lo[8];
; #pragma unroll
;                     for (int e = 0; e < 8; ++e) { hv[e] += av[e]; sq += hv[e] * hv[e]; }
;                     u32x4 wh; wh.x = pk2(hv[0], hv[1]); wh.y = pk2(hv[2], hv[3]); wh.z = pk2(hv[4], hv[5]); wh.w = pk2(hv[6], hv[7]);
;                     lo[0] = hv[0] - bflo(wh.x); lo[1] = hv[1] - bfhi(wh.x); lo[2] = hv[2] - bflo(wh.y); lo[3] = hv[3] - bfhi(wh.y);
;                     lo[4] = hv[4] - bflo(wh.z); lo[5] = hv[5] - bfhi(wh.z); lo[6] = hv[6] - bflo(wh.w); lo[7] = hv[7] - bfhi(wh.w);
;                     u32x4 wl; wl.x = pk2(lo[0], lo[1]); wl.y = pk2(lo[2], lo[3]); wl.z = pk2(lo[4], lo[5]); wl.w = pk2(lo[6], lo[7]);
;                     *(u32x4*)(HO + off) = wh; *(u32x4*)(LO + off) = wl;
;                 }
;                 sq += __shfl_xor(sq, 16); sq += __shfl_xor(sq, 32);
;                 if (fq == 0) ssq_out[(size_t)row * 16 + 4 * u.pn + wc] = sq;
	s_nop 0
	v_mov_b32_e32 v62, v234
	v_mov_b32_e32 v63, v235
	v_mov_b32_e32 v64, v236
	v_mov_b32_e32 v65, v237
	v_rcp_f32_e32 v86, v54
	s_waitcnt vmcnt(2)
	s_nop 0
	v_mov_b32_e32 v66, v230
	v_mov_b32_e32 v67, v231
	v_mov_b32_e32 v68, v232
	v_mov_b32_e32 v69, v233
	v_mul_f32_e32 v54, v55, v88
	v_mul_f32_e32 v54, 0xbfb8aa3b, v54
	v_exp_f32_e32 v54, v54
	s_nop 0
	v_add_f32_e32 v54, 1.0, v54
	v_rcp_f32_e32 v87, v54
	v_mul_f32_e32 v54, v56, v88
	v_rcp_f32_e32 v56, v50
	v_mul_f32_e32 v50, v51, v88
	v_mul_f32_e32 v54, 0xbfb8aa3b, v54
	v_mul_f32_e32 v50, 0xbfb8aa3b, v50
	v_exp_f32_e32 v54, v54
	v_exp_f32_e32 v50, v50
	v_add_f32_e32 v54, 1.0, v54
	v_add_f32_e32 v50, 1.0, v50
	v_rcp_f32_e32 v84, v54
	v_mul_f32_e32 v54, v57, v88
	v_rcp_f32_e32 v57, v50
	v_mul_f32_e32 v50, v52, v88
	v_mul_f32_e32 v54, 0xbfb8aa3b, v54
	v_mul_f32_e32 v50, 0xbfb8aa3b, v50
	v_exp_f32_e32 v54, v54
	v_exp_f32_e32 v50, v50
	v_add_f32_e32 v54, 1.0, v54
	v_add_f32_e32 v50, 1.0, v50
	v_rcp_f32_e32 v85, v54
	v_rcp_f32_e32 v54, v50
	v_mul_f32_e32 v50, v53, v88
	v_mul_f32_e32 v50, 0xbfb8aa3b, v50
	v_exp_f32_e32 v50, v50
	s_waitcnt vmcnt(5)
	v_and_b32_e32 v51, 0xffff0000, v58
	v_add_f32_e32 v50, 1.0, v50
	v_rcp_f32_e32 v55, v50
	v_lshlrev_b32_e32 v50, 16, v58
	s_waitcnt vmcnt(5)
	v_lshlrev_b32_e32 v52, 16, v62
	v_and_b32_e32 v53, 0xffff0000, v62
	v_pk_add_f32 v[50:51], v[50:51], v[52:53]
	s_waitcnt vmcnt(5)
	v_lshlrev_b32_e32 v52, 16, v66
	v_and_b32_e32 v53, 0xffff0000, v66
	v_pk_fma_f32 v[52:53], v[86:87], v[52:53], v[50:51]
	v_lshlrev_b32_e32 v58, 16, v63
	v_cvt_pk_bf16_f32 v50, v52, v53
	v_lshlrev_b32_e32 v86, 16, v50
	v_and_b32_e32 v87, 0xffff0000, v50
	v_pk_mul_f32 v[88:89], v[52:53], v[52:53]
	v_pk_add_f32 v[86:87], v[52:53], v[86:87] neg_lo:[0,1] neg_hi:[0,1]
	v_lshlrev_b32_e32 v52, 16, v59
	v_and_b32_e32 v53, 0xffff0000, v59
	v_and_b32_e32 v59, 0xffff0000, v63
	v_pk_add_f32 v[52:53], v[52:53], v[58:59]
	v_lshlrev_b32_e32 v58, 16, v67
	v_and_b32_e32 v59, 0xffff0000, v67
	v_pk_fma_f32 v[52:53], v[84:85], v[58:59], v[52:53]
	v_lshlrev_b32_e32 v66, 16, v64
	v_cvt_pk_bf16_f32 v51, v52, v53
	v_lshlrev_b32_e32 v62, 16, v51
	v_and_b32_e32 v63, 0xffff0000, v51
	v_pk_mul_f32 v[58:59], v[52:53], v[52:53]
	v_pk_add_f32 v[62:63], v[52:53], v[62:63] neg_lo:[0,1] neg_hi:[0,1]
	v_lshlrev_b32_e32 v52, 16, v60
	v_and_b32_e32 v53, 0xffff0000, v60
	v_and_b32_e32 v67, 0xffff0000, v64
	v_pk_add_f32 v[52:53], v[52:53], v[66:67]
	v_lshlrev_b32_e32 v66, 16, v68
	v_and_b32_e32 v67, 0xffff0000, v68
	v_pk_fma_f32 v[56:57], v[56:57], v[66:67], v[52:53]
	v_add_f32_e32 v53, v74, v75
	v_add_f32_e32 v53, v76, v53
	v_add_f32_e32 v53, v77, v53
	v_add_f32_e32 v53, v78, v53
	v_add_f32_e32 v53, v79, v53
	v_add_f32_e32 v53, v80, v53
	v_add_f32_e32 v53, v81, v53
	v_add_f32_e32 v53, v88, v53
	v_add_f32_e32 v53, v89, v53
	v_lshlrev_b32_e32 v60, 16, v61
	v_and_b32_e32 v61, 0xffff0000, v61
	v_lshlrev_b32_e32 v64, 16, v65
	v_and_b32_e32 v65, 0xffff0000, v65
	v_add_f32_e32 v53, v58, v53
	v_pk_mul_f32 v[66:67], v[56:57], v[56:57]
	v_pk_add_f32 v[60:61], v[60:61], v[64:65]
	v_lshlrev_b32_e32 v64, 16, v69
	v_and_b32_e32 v65, 0xffff0000, v69
	v_add_f32_e32 v53, v59, v53
	v_pk_fma_f32 v[54:55], v[54:55], v[64:65], v[60:61]
	v_add_f32_e32 v53, v66, v53
	v_pk_mul_f32 v[60:61], v[54:55], v[54:55]
	v_add_f32_e32 v53, v67, v53
	v_add_f32_e32 v53, v60, v53
	v_cvt_pk_bf16_f32 v52, v56, v57
	v_add_f32_e32 v60, v61, v53
	v_cvt_pk_bf16_f32 v53, v54, v55
	v_lshlrev_b32_e32 v84, 16, v52
	v_and_b32_e32 v85, 0xffff0000, v52
	v_lshlrev_b32_e32 v58, 16, v53
	v_and_b32_e32 v59, 0xffff0000, v53
	v_pk_add_f32 v[56:57], v[56:57], v[84:85] neg_lo:[0,1] neg_hi:[0,1]
	v_pk_add_f32 v[58:59], v[54:55], v[58:59] neg_lo:[0,1] neg_hi:[0,1]
	v_cvt_pk_bf16_f32 v56, v56, v57
	v_cvt_pk_bf16_f32 v57, v58, v59
	v_lshl_add_u64 v[58:59], s[58:59], 0, v[72:73]
	v_cvt_pk_bf16_f32 v54, v86, v87
	v_cvt_pk_bf16_f32 v55, v62, v63
	global_store_dwordx4 v[58:59], v[50:53], off
	global_store_dwordx4 v[82:83], v[54:57], off
	v_mov_b32_e32 v50, v60
	s_nop 1
	v_permlane16_swap_b32_e32 v60, v50
	s_waitcnt lgkmcnt(0)
	v_add_f32_e32 v50, v60, v50
	ds_bpermute_b32 v51, v145, v50
	s_and_saveexec_b64 s[12:13], s[0:1]
	s_cbranch_execz .LBB0_1348
	v_readlane_b32 s44, v250, 8
	v_readlane_b32 s46, v250, 10
	v_readlane_b32 s47, v250, 11
	s_waitcnt lgkmcnt(0)
	v_add_f32_e32 v52, v50, v51
	s_lshl_b32 s40, s25, 2
	v_lshl_add_u64 v[50:51], s[46:47], 0, v[70:71]
	v_lshl_add_u64 v[50:51], s[54:55], 2, v[50:51]
	v_lshl_add_u64 v[50:51], v[50:51], 0, s[40:41]
	v_readlane_b32 s45, v250, 9
	global_store_dword v[50:51], v52, off
; __device__ __forceinline__ float row_ssq(const float* part, int pitch, int n4, int row, int fq) {
;     __device__ __forceinline__ void operator()(const f32x4 (&acc)[2][2][4][2], const Unit& u, int wr, int wc, int fr, int fq) const {
;     ...
;                 const int row = row0 + ai * HALF + m * 16;
;                 float rs = 0.f; if (GATED) rs = rsqrtf(row_ssq(ssq_in, 16, 4, row, fq) * (1.f / 1024.f) + EPS);
;                 float sq = 0.f;
; #pragma unroll
;                 for (int bj = 0; bj < 2; ++bj) {
;                     const size_t off = (size_t)row * DM + col0 + bj * HALF;
;                     const u32x4 hh = *(const u32x4*)(HI + off), ll = *(const u32x4*)(LO + off);
;                     float hv[8] = {bflo(hh.x) + bflo(ll.x), bfhi(hh.x) + bfhi(ll.x), bflo(hh.y) + bflo(ll.y), bfhi(hh.y) + bfhi(ll.y),
;                                    bflo(hh.z) + bflo(ll.z), bfhi(hh.z) + bfhi(ll.z), bflo(hh.w) + bflo(ll.w), bfhi(hh.w) + bfhi(ll.w)};
;                     float av[8] = {acc[ai][bj][m][0][0], acc[ai][bj][m][0][1], acc[ai][bj][m][0][2], acc[ai][bj][m][0][3], acc[ai][bj][m][1][0], acc[ai][bj][m][1][1], acc[ai][bj][m][1][2], acc[ai][bj][m][1][3]};
;                     if (GATED) { const u32x4 pp = *(const u32x4*)(PP + off);
;                         const float pv[8] = {bflo(pp.x), bfhi(pp.x), bflo(pp.y), bfhi(pp.y), bflo(pp.z), bfhi(pp.z), bflo(pp.w), bfhi(pp.w)};
; #pragma unroll
;                         for (int e = 0; e < 8; ++e) av[e] = fast_sigmoid(av[e] * rs) * pv[e]; }
;                     else {
; #pragma unroll
;                         for (int e = 0; e < 8; ++e) av[e] *= alpha; }
;                     float lo[8];
; #pragma unroll
;                     for (int e = 0; e < 8; ++e) { hv[e] += av[e]; sq += hv[e] * hv[e]; }
;                     u32x4 wh; wh.x = pk2(hv[0], hv[1]); wh.y = pk2(hv[2], hv[3]); wh.z = pk2(hv[4], hv[5]); wh.w = pk2(hv[6], hv[7]);
;                     lo[0] = hv[0] - bflo(wh.x); lo[1] = hv[1] - bfhi(wh.x); lo[2] = hv[2] - bflo(wh.y); lo[3] = hv[3] - bfhi(wh.y);
;                     lo[4] = hv[4] - bflo(wh.z); lo[5] = hv[5] - bfhi(wh.z); lo[6] = hv[6] - bflo(wh.w); lo[7] = hv[7] - bfhi(wh.w);
;                     u32x4 wl; wl.x = pk2(lo[0], lo[1]); wl.y = pk2(lo[2], lo[3]); wl.z = pk2(lo[4], lo[5]); wl.w = pk2(lo[6], lo[7]);
;                     *(u32x4*)(HO + off) = wh; *(u32x4*)(LO + off) = wl;
.LBB0_1348:
	s_or_b64 exec, exec, s[12:13]
	v_add_u32_e32 v56, 0x90, v144
	v_ashrrev_i32_e32 v57, 31, v56
	v_lshlrev_b64 v[54:55], 6, v[56:57]
	s_waitcnt lgkmcnt(0)
	v_lshl_add_u64 v[50:51], v[136:137], 0, v[54:55]
	global_load_dwordx4 v[50:53], v[50:51], off
	v_readlane_b32 s10, v253, 35
	v_readlane_b32 s11, v253, 36
	v_readlane_b32 s6, v250, 49
	v_readlane_b32 s7, v250, 50
	s_waitcnt vmcnt(0)
	v_mov_b32_e32 v58, v51
	v_mov_b32_e32 v59, v52
	v_mov_b32_e32 v51, v53
	v_pk_add_f32 v[50:51], v[58:59], v[50:51]
	s_nop 0
	v_add_f32_e32 v50, v50, v51
	v_mov_b32_e32 v51, v50
	s_nop 1
	v_permlane16_swap_b32_e32 v50, v51
	s_waitcnt lgkmcnt(0)
	v_add_f32_e32 v50, v50, v51
	v_mov_b32_e32 v51, v50
	s_nop 1
	v_permlane32_swap_b32_e32 v50, v51
	s_waitcnt lgkmcnt(0)
	v_add_f32_e32 v50, v50, v51
	v_fmamk_f32 v50, v50, 0x3a800000, v239
	v_cmp_gt_f32_e32 vcc, s16, v50
	v_mul_f32_e32 v51, 0x4b800000, v50
	s_nop 0
	v_cndmask_b32_e32 v50, v50, v51, vcc
	v_rsq_f32_e32 v50, v50
	s_nop 0
	v_mul_f32_e32 v51, 0x45800000, v50
	v_cndmask_b32_e32 v72, v50, v51, vcc
	v_lshlrev_b64 v[50:51], 10, v[56:57]
	v_lshl_add_u64 v[50:51], v[50:51], 0, v[142:143]
	v_lshlrev_b64 v[56:57], 1, v[50:51]
	v_lshl_add_u64 v[50:51], s[10:11], 0, v[56:57]
	v_lshl_add_u64 v[52:53], s[14:15], 0, v[56:57]
	global_load_dwordx4 v[62:65], v[50:51], off
	global_load_dwordx4 v[74:77], v[52:53], off
	v_lshl_add_u64 v[50:51], s[6:7], 0, v[56:57]
	global_load_dwordx4 v[66:69], v[50:51], off
	global_load_dwordx4 v[226:229], v56, s[10:11] offset:256
	global_load_dwordx4 v[234:237], v56, s[6:7] offset:256
	global_load_dwordx4 v[230:233], v56, s[14:15] offset:256
	v_mul_f32_e32 v42, v42, v72
	v_mul_f32_e32 v42, 0xbfb8aa3b, v42
	v_exp_f32_e32 v42, v42
	v_mul_f32_e32 v46, v46, v72
	v_mul_f32_e32 v47, v47, v72
	v_mul_f32_e32 v46, 0xbfb8aa3b, v46
	v_add_f32_e32 v42, 1.0, v42
	v_rcp_f32_e32 v52, v42
	v_mul_f32_e32 v42, v43, v72
	v_mul_f32_e32 v42, 0xbfb8aa3b, v42
	v_exp_f32_e32 v42, v42
	v_mul_f32_e32 v47, 0xbfb8aa3b, v47
	v_exp_f32_e32 v46, v46
	v_exp_f32_e32 v47, v47
	v_add_f32_e32 v42, 1.0, v42
	v_rcp_f32_e32 v53, v42
	v_mul_f32_e32 v42, v44, v72
	v_mul_f32_e32 v42, 0xbfb8aa3b, v42
	v_exp_f32_e32 v42, v42
	v_mul_f32_e32 v48, v48, v72
	v_mul_f32_e32 v49, v49, v72
	v_add_f32_e32 v46, 1.0, v46
	v_add_f32_e32 v42, 1.0, v42
	v_rcp_f32_e32 v70, v42
	v_mul_f32_e32 v42, v45, v72
	v_mul_f32_e32 v42, 0xbfb8aa3b, v42
	v_exp_f32_e32 v42, v42
	v_add_f32_e32 v47, 1.0, v47
	v_mul_f32_e32 v48, 0xbfb8aa3b, v48
	v_mul_f32_e32 v49, 0xbfb8aa3b, v49
	v_rcp_f32_e32 v46, v46
	v_rcp_f32_e32 v47, v47
	v_exp_f32_e32 v48, v48
	v_exp_f32_e32 v49, v49
	v_add_f32_e32 v42, 1.0, v42
	v_rcp_f32_e32 v71, v42
	v_add_f32_e32 v48, 1.0, v48
	v_add_f32_e32 v49, 1.0, v49
	v_rcp_f32_e32 v48, v48
	v_rcp_f32_e32 v49, v49
	v_mul_f32_e32 v38, v38, v72
	v_mul_f32_e32 v38, 0xbfb8aa3b, v38
	v_exp_f32_e32 v38, v38
	v_mul_f32_e32 v34, v34, v72
	v_mul_f32_e32 v34, 0xbfb8aa3b, v34
	v_exp_f32_e32 v34, v34
	v_add_f32_e32 v38, 1.0, v38
	v_add_f32_e32 v34, 1.0, v34
	s_waitcnt vmcnt(5)
	v_lshlrev_b32_e32 v42, 16, v62
	v_and_b32_e32 v43, 0xffff0000, v62
	s_waitcnt vmcnt(3)
	v_lshlrev_b32_e32 v44, 16, v66
	v_and_b32_e32 v45, 0xffff0000, v66
	v_pk_add_f32 v[42:43], v[42:43], v[44:45]
	v_lshlrev_b32_e32 v44, 16, v74
	v_and_b32_e32 v45, 0xffff0000, v74
	v_pk_fma_f32 v[44:45], v[46:47], v[44:45], v[42:43]
	v_lshlrev_b32_e32 v60, 16, v67
	v_cvt_pk_bf16_f32 v42, v44, v45
	v_lshlrev_b32_e32 v46, 16, v42
	v_and_b32_e32 v47, 0xffff0000, v42
	v_pk_mul_f32 v[58:59], v[44:45], v[44:45]
	v_pk_add_f32 v[46:47], v[44:45], v[46:47] neg_lo:[0,1] neg_hi:[0,1]
	v_lshlrev_b32_e32 v44, 16, v63
	v_and_b32_e32 v45, 0xffff0000, v63
	v_and_b32_e32 v61, 0xffff0000, v67
	v_pk_add_f32 v[44:45], v[44:45], v[60:61]
	v_lshlrev_b32_e32 v60, 16, v75
	v_and_b32_e32 v61, 0xffff0000, v75
	v_pk_fma_f32 v[44:45], v[48:49], v[60:61], v[44:45]
	v_lshlrev_b32_e32 v62, 16, v68
	v_cvt_pk_bf16_f32 v43, v44, v45
	v_lshlrev_b32_e32 v48, 16, v43
	v_and_b32_e32 v49, 0xffff0000, v43
	v_pk_mul_f32 v[60:61], v[44:45], v[44:45]
	v_pk_add_f32 v[48:49], v[44:45], v[48:49] neg_lo:[0,1] neg_hi:[0,1]
	v_lshlrev_b32_e32 v44, 16, v64
	v_and_b32_e32 v45, 0xffff0000, v64
	v_and_b32_e32 v63, 0xffff0000, v68
	v_pk_add_f32 v[44:45], v[44:45], v[62:63]
	v_lshlrev_b32_e32 v62, 16, v76
	v_and_b32_e32 v63, 0xffff0000, v76
	v_pk_fma_f32 v[52:53], v[52:53], v[62:63], v[44:45]
	v_lshlrev_b32_e32 v64, 16, v65
	v_cvt_pk_bf16_f32 v44, v52, v53
	v_lshlrev_b32_e32 v66, 16, v44
	v_and_b32_e32 v67, 0xffff0000, v44
	v_pk_mul_f32 v[62:63], v[52:53], v[52:53]
	v_pk_add_f32 v[52:53], v[52:53], v[66:67] neg_lo:[0,1] neg_hi:[0,1]
	v_and_b32_e32 v65, 0xffff0000, v65
	v_lshlrev_b32_e32 v66, 16, v69
	v_and_b32_e32 v67, 0xffff0000, v69
	v_pk_add_f32 v[64:65], v[64:65], v[66:67]
	v_lshlrev_b32_e32 v66, 16, v77
	v_and_b32_e32 v67, 0xffff0000, v77
	v_pk_fma_f32 v[66:67], v[70:71], v[66:67], v[64:65]
	v_cvt_pk_bf16_f32 v46, v46, v47
	v_cvt_pk_bf16_f32 v45, v66, v67
	v_lshlrev_b32_e32 v68, 16, v45
	v_and_b32_e32 v69, 0xffff0000, v45
	v_pk_mul_f32 v[64:65], v[66:67], v[66:67]
	v_pk_add_f32 v[66:67], v[66:67], v[68:69] neg_lo:[0,1] neg_hi:[0,1]
	v_cvt_pk_bf16_f32 v47, v48, v49
	v_cvt_pk_bf16_f32 v48, v52, v53
	v_lshl_add_u64 v[52:53], s[58:59], 0, v[56:57]
	v_or_b32_e32 v56, 0x100, v56
	v_cvt_pk_bf16_f32 v49, v66, v67
	global_store_dwordx4 v[52:53], v[42:45], off
	global_store_dwordx4 v[50:51], v[46:49], off
	v_lshl_add_u64 v[66:67], s[6:7], 0, v[56:57]
	v_lshl_add_u64 v[42:43], s[10:11], 0, v[56:57]
	s_waitcnt vmcnt(4)
	s_nop 0
	v_mov_b32_e32 v42, v226
	v_mov_b32_e32 v43, v227
	v_mov_b32_e32 v44, v228
	v_mov_b32_e32 v45, v229
	v_lshl_add_u64 v[50:51], s[14:15], 0, v[56:57]
	s_waitcnt vmcnt(3)
; __device__ __forceinline__ float bflo(unsigned u) { return __uint_as_float(u << 16); }
;     __device__ __forceinline__ void operator()(const f32x4 (&acc)[2][2][4][2], const Unit& u, int wr, int wc, int fr, int fq) const {
;     ...
;                 for (int bj = 0; bj < 2; ++bj) {
;                     const size_t off = (size_t)row * DM + col0 + bj * HALF;
;                     const u32x4 hh = *(const u32x4*)(HI + off), ll = *(const u32x4*)(LO + off);
;                     float hv[8] = {bflo(hh.x) + bflo(ll.x), bfhi(hh.x) + bfhi(ll.x), bflo(hh.y) + bflo(ll.y), bfhi(hh.y) + bfhi(ll.y),
;                                    bflo(hh.z) + bflo(ll.z), bfhi(hh.z) + bfhi(ll.z), bflo(hh.w) + bflo(ll.w), bfhi(hh.w) + bfhi(ll.w)};
;                     float av[8] = {acc[ai][bj][m][0][0], acc[ai][bj][m][0][1], acc[ai][bj][m][0][2], acc[ai][bj][m][0][3], acc[ai][bj][m][1][0], acc[ai][bj][m][1][1], acc[ai][bj][m][1][2], acc[ai][bj][m][1][3]};
;                     if (GATED) { const u32x4 pp = *(const u32x4*)(PP + off);
;                         const float pv[8] = {bflo(pp.x), bfhi(pp.x), bflo(pp.y), bfhi(pp.y), bflo(pp.z), bfhi(pp.z), bflo(pp.w), bfhi(pp.w)};
; #pragma unroll
;                         for (int e = 0; e < 8; ++e) av[e] = fast_sigmoid(av[e] * rs) * pv[e]; }
;                     else {
; #pragma unroll
;                         for (int e = 0; e < 8; ++e) av[e] *= alpha; }
;                     float lo[8];
; #pragma unroll
;                     for (int e = 0; e < 8; ++e) { hv[e] += av[e]; sq += hv[e] * hv[e]; }
;                     u32x4 wh; wh.x = pk2(hv[0], hv[1]); wh.y = pk2(hv[2], hv[3]); wh.z = pk2(hv[4], hv[5]); wh.w = pk2(hv[6], hv[7]);
;                     lo[0] = hv[0] - bflo(wh.x); lo[1] = hv[1] - bfhi(wh.x); lo[2] = hv[2] - bflo(wh.y); lo[3] = hv[3] - bfhi(wh.y);
;                     lo[4] = hv[4] - bflo(wh.z); lo[5] = hv[5] - bfhi(wh.z); lo[6] = hv[6] - bflo(wh.w); lo[7] = hv[7] - bfhi(wh.w);
;                     u32x4 wl; wl.x = pk2(lo[0], lo[1]); wl.y = pk2(lo[2], lo[3]); wl.z = pk2(lo[4], lo[5]); wl.w = pk2(lo[6], lo[7]);
;                     *(u32x4*)(HO + off) = wh; *(u32x4*)(LO + off) = wl;
;                 }
;                 sq += __shfl_xor(sq, 16); sq += __shfl_xor(sq, 32);
;                 if (fq == 0) ssq_out[(size_t)row * 16 + 4 * u.pn + wc] = sq;
	s_nop 0
	v_mov_b32_e32 v46, v234
	v_mov_b32_e32 v47, v235
	v_mov_b32_e32 v48, v236
	v_mov_b32_e32 v49, v237
	v_rcp_f32_e32 v70, v38
	s_waitcnt vmcnt(2)
	s_nop 0
	v_mov_b32_e32 v50, v230
	v_mov_b32_e32 v51, v231
	v_mov_b32_e32 v52, v232
	v_mov_b32_e32 v53, v233
	v_mul_f32_e32 v38, v39, v72
	v_mul_f32_e32 v38, 0xbfb8aa3b, v38
	v_exp_f32_e32 v38, v38
	s_nop 0
	v_add_f32_e32 v38, 1.0, v38
	v_rcp_f32_e32 v71, v38
	v_mul_f32_e32 v38, v40, v72
	v_rcp_f32_e32 v40, v34
	v_mul_f32_e32 v34, v35, v72
	v_mul_f32_e32 v38, 0xbfb8aa3b, v38
	v_mul_f32_e32 v34, 0xbfb8aa3b, v34
	v_exp_f32_e32 v38, v38
	v_exp_f32_e32 v34, v34
	v_add_f32_e32 v38, 1.0, v38
	v_add_f32_e32 v34, 1.0, v34
	v_rcp_f32_e32 v68, v38
	v_mul_f32_e32 v38, v41, v72
	v_rcp_f32_e32 v41, v34
	v_mul_f32_e32 v34, v36, v72
	v_mul_f32_e32 v38, 0xbfb8aa3b, v38
	v_mul_f32_e32 v34, 0xbfb8aa3b, v34
	v_exp_f32_e32 v38, v38
	v_exp_f32_e32 v34, v34
	v_add_f32_e32 v38, 1.0, v38
	v_add_f32_e32 v34, 1.0, v34
	v_rcp_f32_e32 v69, v38
	v_rcp_f32_e32 v38, v34
	v_mul_f32_e32 v34, v37, v72
	v_mul_f32_e32 v34, 0xbfb8aa3b, v34
	v_exp_f32_e32 v34, v34
	s_waitcnt vmcnt(5)
	v_and_b32_e32 v35, 0xffff0000, v42
	v_add_f32_e32 v34, 1.0, v34
	v_rcp_f32_e32 v39, v34
	v_lshlrev_b32_e32 v34, 16, v42
	s_waitcnt vmcnt(5)
	v_lshlrev_b32_e32 v36, 16, v46
	v_and_b32_e32 v37, 0xffff0000, v46
	v_pk_add_f32 v[34:35], v[34:35], v[36:37]
	s_waitcnt vmcnt(5)
	v_lshlrev_b32_e32 v36, 16, v50
	v_and_b32_e32 v37, 0xffff0000, v50
	v_pk_fma_f32 v[36:37], v[70:71], v[36:37], v[34:35]
	v_lshlrev_b32_e32 v42, 16, v47
	v_cvt_pk_bf16_f32 v34, v36, v37
	v_lshlrev_b32_e32 v70, 16, v34
	v_and_b32_e32 v71, 0xffff0000, v34
	v_pk_mul_f32 v[72:73], v[36:37], v[36:37]
	v_pk_add_f32 v[70:71], v[36:37], v[70:71] neg_lo:[0,1] neg_hi:[0,1]
	v_lshlrev_b32_e32 v36, 16, v43
	v_and_b32_e32 v37, 0xffff0000, v43
	v_and_b32_e32 v43, 0xffff0000, v47
	v_pk_add_f32 v[36:37], v[36:37], v[42:43]
	v_lshlrev_b32_e32 v42, 16, v51
	v_and_b32_e32 v43, 0xffff0000, v51
	v_pk_fma_f32 v[36:37], v[68:69], v[42:43], v[36:37]
	v_lshlrev_b32_e32 v50, 16, v48
	v_cvt_pk_bf16_f32 v35, v36, v37
	v_lshlrev_b32_e32 v46, 16, v35
	v_and_b32_e32 v47, 0xffff0000, v35
	v_pk_mul_f32 v[42:43], v[36:37], v[36:37]
	v_pk_add_f32 v[46:47], v[36:37], v[46:47] neg_lo:[0,1] neg_hi:[0,1]
	v_lshlrev_b32_e32 v36, 16, v44
	v_and_b32_e32 v37, 0xffff0000, v44
	v_and_b32_e32 v51, 0xffff0000, v48
	v_pk_add_f32 v[36:37], v[36:37], v[50:51]
	v_lshlrev_b32_e32 v50, 16, v52
	v_and_b32_e32 v51, 0xffff0000, v52
	v_pk_fma_f32 v[40:41], v[40:41], v[50:51], v[36:37]
	v_add_f32_e32 v37, v58, v59
	v_add_f32_e32 v37, v60, v37
	v_add_f32_e32 v37, v61, v37
	v_add_f32_e32 v37, v62, v37
	v_add_f32_e32 v37, v63, v37
	v_add_f32_e32 v37, v64, v37
	v_add_f32_e32 v37, v65, v37
	v_add_f32_e32 v37, v72, v37
	v_add_f32_e32 v37, v73, v37
	v_lshlrev_b32_e32 v44, 16, v45
	v_and_b32_e32 v45, 0xffff0000, v45
	v_lshlrev_b32_e32 v48, 16, v49
	v_and_b32_e32 v49, 0xffff0000, v49
	v_add_f32_e32 v37, v42, v37
	v_pk_mul_f32 v[50:51], v[40:41], v[40:41]
	v_pk_add_f32 v[44:45], v[44:45], v[48:49]
	v_lshlrev_b32_e32 v48, 16, v53
	v_and_b32_e32 v49, 0xffff0000, v53
	v_add_f32_e32 v37, v43, v37
	v_pk_fma_f32 v[38:39], v[38:39], v[48:49], v[44:45]
	v_add_f32_e32 v37, v50, v37
	v_pk_mul_f32 v[44:45], v[38:39], v[38:39]
	v_add_f32_e32 v37, v51, v37
	v_add_f32_e32 v37, v44, v37
	v_cvt_pk_bf16_f32 v36, v40, v41
	v_add_f32_e32 v44, v45, v37
	v_cvt_pk_bf16_f32 v37, v38, v39
	v_lshlrev_b32_e32 v68, 16, v36
	v_and_b32_e32 v69, 0xffff0000, v36
	v_lshlrev_b32_e32 v42, 16, v37
	v_and_b32_e32 v43, 0xffff0000, v37
	v_pk_add_f32 v[40:41], v[40:41], v[68:69] neg_lo:[0,1] neg_hi:[0,1]
	v_pk_add_f32 v[42:43], v[38:39], v[42:43] neg_lo:[0,1] neg_hi:[0,1]
	v_cvt_pk_bf16_f32 v40, v40, v41
	v_cvt_pk_bf16_f32 v41, v42, v43
	v_lshl_add_u64 v[42:43], s[58:59], 0, v[56:57]
	v_cvt_pk_bf16_f32 v38, v70, v71
	v_cvt_pk_bf16_f32 v39, v46, v47
	global_store_dwordx4 v[42:43], v[34:37], off
	global_store_dwordx4 v[66:67], v[38:41], off
	v_mov_b32_e32 v34, v44
	s_nop 1
	v_permlane16_swap_b32_e32 v44, v34
	s_waitcnt lgkmcnt(0)
	v_add_f32_e32 v34, v44, v34
	ds_bpermute_b32 v35, v145, v34
	s_and_saveexec_b64 s[12:13], s[0:1]
	s_cbranch_execz .LBB0_1350
	v_readlane_b32 s44, v250, 8
	v_readlane_b32 s46, v250, 10
	v_readlane_b32 s47, v250, 11
	s_waitcnt lgkmcnt(0)
	v_add_f32_e32 v36, v34, v35
	s_lshl_b32 s40, s25, 2
	v_lshl_add_u64 v[34:35], s[46:47], 0, v[54:55]
	v_lshl_add_u64 v[34:35], s[54:55], 2, v[34:35]
	v_lshl_add_u64 v[34:35], v[34:35], 0, s[40:41]
	v_readlane_b32 s45, v250, 9
	global_store_dword v[34:35], v36, off
; __device__ __forceinline__ float row_ssq(const float* part, int pitch, int n4, int row, int fq) {
;     __device__ __forceinline__ void operator()(const f32x4 (&acc)[2][2][4][2], const Unit& u, int wr, int wc, int fr, int fq) const {
;     ...
;                 const int row = row0 + ai * HALF + m * 16;
;                 float rs = 0.f; if (GATED) rs = rsqrtf(row_ssq(ssq_in, 16, 4, row, fq) * (1.f / 1024.f) + EPS);
;                 float sq = 0.f;
; #pragma unroll
;                 for (int bj = 0; bj < 2; ++bj) {
;                     const size_t off = (size_t)row * DM + col0 + bj * HALF;
;                     const u32x4 hh = *(const u32x4*)(HI + off), ll = *(const u32x4*)(LO + off);
;                     float hv[8] = {bflo(hh.x) + bflo(ll.x), bfhi(hh.x) + bfhi(ll.x), bflo(hh.y) + bflo(ll.y), bfhi(hh.y) + bfhi(ll.y),
;                                    bflo(hh.z) + bflo(ll.z), bfhi(hh.z) + bfhi(ll.z), bflo(hh.w) + bflo(ll.w), bfhi(hh.w) + bfhi(ll.w)};
;                     float av[8] = {acc[ai][bj][m][0][0], acc[ai][bj][m][0][1], acc[ai][bj][m][0][2], acc[ai][bj][m][0][3], acc[ai][bj][m][1][0], acc[ai][bj][m][1][1], acc[ai][bj][m][1][2], acc[ai][bj][m][1][3]};
;                     if (GATED) { const u32x4 pp = *(const u32x4*)(PP + off);
;                         const float pv[8] = {bflo(pp.x), bfhi(pp.x), bflo(pp.y), bfhi(pp.y), bflo(pp.z), bfhi(pp.z), bflo(pp.w), bfhi(pp.w)};
; #pragma unroll
;                         for (int e = 0; e < 8; ++e) av[e] = fast_sigmoid(av[e] * rs) * pv[e]; }
;                     else {
; #pragma unroll
;                         for (int e = 0; e < 8; ++e) av[e] *= alpha; }
;                     float lo[8];
; #pragma unroll
;                     for (int e = 0; e < 8; ++e) { hv[e] += av[e]; sq += hv[e] * hv[e]; }
;                     u32x4 wh; wh.x = pk2(hv[0], hv[1]); wh.y = pk2(hv[2], hv[3]); wh.z = pk2(hv[4], hv[5]); wh.w = pk2(hv[6], hv[7]);
;                     lo[0] = hv[0] - bflo(wh.x); lo[1] = hv[1] - bfhi(wh.x); lo[2] = hv[2] - bflo(wh.y); lo[3] = hv[3] - bfhi(wh.y);
;                     lo[4] = hv[4] - bflo(wh.z); lo[5] = hv[5] - bfhi(wh.z); lo[6] = hv[6] - bflo(wh.w); lo[7] = hv[7] - bfhi(wh.w);
;                     u32x4 wl; wl.x = pk2(lo[0], lo[1]); wl.y = pk2(lo[2], lo[3]); wl.z = pk2(lo[4], lo[5]); wl.w = pk2(lo[6], lo[7]);
;                     *(u32x4*)(HO + off) = wh; *(u32x4*)(LO + off) = wl;
.LBB0_1350:
	s_or_b64 exec, exec, s[12:13]
	v_add_u32_e32 v40, 0xa0, v144
	v_ashrrev_i32_e32 v41, 31, v40
	v_lshlrev_b64 v[38:39], 6, v[40:41]
	s_waitcnt lgkmcnt(0)
	v_lshl_add_u64 v[34:35], v[136:137], 0, v[38:39]
	global_load_dwordx4 v[34:37], v[34:35], off
	v_readlane_b32 s10, v253, 35
	v_readlane_b32 s11, v253, 36
	v_readlane_b32 s6, v250, 49
	v_readlane_b32 s7, v250, 50
	s_waitcnt vmcnt(0)
	v_mov_b32_e32 v42, v35
	v_mov_b32_e32 v43, v36
	v_mov_b32_e32 v35, v37
	v_pk_add_f32 v[34:35], v[42:43], v[34:35]
	s_nop 0
	v_add_f32_e32 v34, v34, v35
	v_mov_b32_e32 v35, v34
	s_nop 1
	v_permlane16_swap_b32_e32 v34, v35
	s_waitcnt lgkmcnt(0)
	v_add_f32_e32 v34, v34, v35
	v_mov_b32_e32 v35, v34
	s_nop 1
	v_permlane32_swap_b32_e32 v34, v35
	s_waitcnt lgkmcnt(0)
	v_add_f32_e32 v34, v34, v35
	v_fmamk_f32 v34, v34, 0x3a800000, v239
	v_cmp_gt_f32_e32 vcc, s16, v34
	v_mul_f32_e32 v35, 0x4b800000, v34
	s_nop 0
	v_cndmask_b32_e32 v34, v34, v35, vcc
	v_rsq_f32_e32 v34, v34
	s_nop 0
	v_mul_f32_e32 v35, 0x45800000, v34
	v_cndmask_b32_e32 v56, v34, v35, vcc
	v_lshlrev_b64 v[34:35], 10, v[40:41]
	v_lshl_add_u64 v[34:35], v[34:35], 0, v[142:143]
	v_lshlrev_b64 v[40:41], 1, v[34:35]
	v_lshl_add_u64 v[34:35], s[10:11], 0, v[40:41]
	v_lshl_add_u64 v[36:37], s[14:15], 0, v[40:41]
	global_load_dwordx4 v[46:49], v[34:35], off
	global_load_dwordx4 v[58:61], v[36:37], off
	v_lshl_add_u64 v[34:35], s[6:7], 0, v[40:41]
	global_load_dwordx4 v[50:53], v[34:35], off
	global_load_dwordx4 v[226:229], v40, s[10:11] offset:256
	global_load_dwordx4 v[234:237], v40, s[6:7] offset:256
	global_load_dwordx4 v[230:233], v40, s[14:15] offset:256
	v_mul_f32_e32 v26, v26, v56
	v_mul_f32_e32 v26, 0xbfb8aa3b, v26
	v_exp_f32_e32 v26, v26
	v_mul_f32_e32 v30, v30, v56
	v_mul_f32_e32 v31, v31, v56
	v_mul_f32_e32 v30, 0xbfb8aa3b, v30
	v_add_f32_e32 v26, 1.0, v26
	v_rcp_f32_e32 v36, v26
	v_mul_f32_e32 v26, v27, v56
	v_mul_f32_e32 v26, 0xbfb8aa3b, v26
	v_exp_f32_e32 v26, v26
	v_mul_f32_e32 v31, 0xbfb8aa3b, v31
	v_exp_f32_e32 v30, v30
	v_exp_f32_e32 v31, v31
	v_add_f32_e32 v26, 1.0, v26
	v_rcp_f32_e32 v37, v26
	v_mul_f32_e32 v26, v28, v56
	v_mul_f32_e32 v26, 0xbfb8aa3b, v26
	v_exp_f32_e32 v26, v26
	v_mul_f32_e32 v32, v32, v56
	v_mul_f32_e32 v33, v33, v56
	v_add_f32_e32 v30, 1.0, v30
	v_add_f32_e32 v26, 1.0, v26
	v_rcp_f32_e32 v54, v26
	v_mul_f32_e32 v26, v29, v56
	v_mul_f32_e32 v26, 0xbfb8aa3b, v26
	v_exp_f32_e32 v26, v26
	v_add_f32_e32 v31, 1.0, v31
	v_mul_f32_e32 v32, 0xbfb8aa3b, v32
	v_mul_f32_e32 v33, 0xbfb8aa3b, v33
	v_rcp_f32_e32 v30, v30
	v_rcp_f32_e32 v31, v31
	v_exp_f32_e32 v32, v32
	v_exp_f32_e32 v33, v33
	v_add_f32_e32 v26, 1.0, v26
	v_rcp_f32_e32 v55, v26
	v_add_f32_e32 v32, 1.0, v32
	v_add_f32_e32 v33, 1.0, v33
	v_rcp_f32_e32 v32, v32
	v_rcp_f32_e32 v33, v33
	v_mul_f32_e32 v22, v22, v56
	v_mul_f32_e32 v22, 0xbfb8aa3b, v22
	v_exp_f32_e32 v22, v22
	v_mul_f32_e32 v18, v18, v56
	v_mul_f32_e32 v18, 0xbfb8aa3b, v18
	v_exp_f32_e32 v18, v18
	v_add_f32_e32 v22, 1.0, v22
	v_add_f32_e32 v18, 1.0, v18
	s_waitcnt vmcnt(5)
	v_lshlrev_b32_e32 v26, 16, v46
	v_and_b32_e32 v27, 0xffff0000, v46
	s_waitcnt vmcnt(3)
	v_lshlrev_b32_e32 v28, 16, v50
	v_and_b32_e32 v29, 0xffff0000, v50
	v_pk_add_f32 v[26:27], v[26:27], v[28:29]
	v_lshlrev_b32_e32 v28, 16, v58
	v_and_b32_e32 v29, 0xffff0000, v58
	v_pk_fma_f32 v[28:29], v[30:31], v[28:29], v[26:27]
	v_lshlrev_b32_e32 v44, 16, v51
	v_cvt_pk_bf16_f32 v26, v28, v29
	v_lshlrev_b32_e32 v30, 16, v26
	v_and_b32_e32 v31, 0xffff0000, v26
	v_pk_mul_f32 v[42:43], v[28:29], v[28:29]
	v_pk_add_f32 v[30:31], v[28:29], v[30:31] neg_lo:[0,1] neg_hi:[0,1]
	v_lshlrev_b32_e32 v28, 16, v47
	v_and_b32_e32 v29, 0xffff0000, v47
	v_and_b32_e32 v45, 0xffff0000, v51
	v_pk_add_f32 v[28:29], v[28:29], v[44:45]
	v_lshlrev_b32_e32 v44, 16, v59
	v_and_b32_e32 v45, 0xffff0000, v59
	v_pk_fma_f32 v[28:29], v[32:33], v[44:45], v[28:29]
	v_lshlrev_b32_e32 v46, 16, v52
	v_cvt_pk_bf16_f32 v27, v28, v29
	v_lshlrev_b32_e32 v32, 16, v27
	v_and_b32_e32 v33, 0xffff0000, v27
	v_pk_mul_f32 v[44:45], v[28:29], v[28:29]
	v_pk_add_f32 v[32:33], v[28:29], v[32:33] neg_lo:[0,1] neg_hi:[0,1]
	v_lshlrev_b32_e32 v28, 16, v48
	v_and_b32_e32 v29, 0xffff0000, v48
	v_and_b32_e32 v47, 0xffff0000, v52
	v_pk_add_f32 v[28:29], v[28:29], v[46:47]
	v_lshlrev_b32_e32 v46, 16, v60
	v_and_b32_e32 v47, 0xffff0000, v60
	v_pk_fma_f32 v[36:37], v[36:37], v[46:47], v[28:29]
	v_lshlrev_b32_e32 v48, 16, v49
	v_cvt_pk_bf16_f32 v28, v36, v37
	v_lshlrev_b32_e32 v50, 16, v28
	v_and_b32_e32 v51, 0xffff0000, v28
	v_pk_mul_f32 v[46:47], v[36:37], v[36:37]
	v_pk_add_f32 v[36:37], v[36:37], v[50:51] neg_lo:[0,1] neg_hi:[0,1]
	v_and_b32_e32 v49, 0xffff0000, v49
	v_lshlrev_b32_e32 v50, 16, v53
	v_and_b32_e32 v51, 0xffff0000, v53
	v_pk_add_f32 v[48:49], v[48:49], v[50:51]
	v_lshlrev_b32_e32 v50, 16, v61
	v_and_b32_e32 v51, 0xffff0000, v61
	v_pk_fma_f32 v[50:51], v[54:55], v[50:51], v[48:49]
	v_cvt_pk_bf16_f32 v30, v30, v31
	v_cvt_pk_bf16_f32 v29, v50, v51
	v_lshlrev_b32_e32 v52, 16, v29
	v_and_b32_e32 v53, 0xffff0000, v29
	v_pk_mul_f32 v[48:49], v[50:51], v[50:51]
	v_pk_add_f32 v[50:51], v[50:51], v[52:53] neg_lo:[0,1] neg_hi:[0,1]
	v_cvt_pk_bf16_f32 v31, v32, v33
	v_cvt_pk_bf16_f32 v32, v36, v37
	v_lshl_add_u64 v[36:37], s[58:59], 0, v[40:41]
	v_or_b32_e32 v40, 0x100, v40
	v_cvt_pk_bf16_f32 v33, v50, v51
	global_store_dwordx4 v[36:37], v[26:29], off
	global_store_dwordx4 v[34:35], v[30:33], off
	v_lshl_add_u64 v[50:51], s[6:7], 0, v[40:41]
	v_lshl_add_u64 v[26:27], s[10:11], 0, v[40:41]
	s_waitcnt vmcnt(4)
	s_nop 0
	v_mov_b32_e32 v26, v226
	v_mov_b32_e32 v27, v227
	v_mov_b32_e32 v28, v228
	v_mov_b32_e32 v29, v229
	v_lshl_add_u64 v[34:35], s[14:15], 0, v[40:41]
	s_waitcnt vmcnt(3)
; __device__ __forceinline__ float bflo(unsigned u) { return __uint_as_float(u << 16); }
;     __device__ __forceinline__ void operator()(const f32x4 (&acc)[2][2][4][2], const Unit& u, int wr, int wc, int fr, int fq) const {
;     ...
;                 for (int bj = 0; bj < 2; ++bj) {
;                     const size_t off = (size_t)row * DM + col0 + bj * HALF;
;                     const u32x4 hh = *(const u32x4*)(HI + off), ll = *(const u32x4*)(LO + off);
;                     float hv[8] = {bflo(hh.x) + bflo(ll.x), bfhi(hh.x) + bfhi(ll.x), bflo(hh.y) + bflo(ll.y), bfhi(hh.y) + bfhi(ll.y),
;                                    bflo(hh.z) + bflo(ll.z), bfhi(hh.z) + bfhi(ll.z), bflo(hh.w) + bflo(ll.w), bfhi(hh.w) + bfhi(ll.w)};
;                     float av[8] = {acc[ai][bj][m][0][0], acc[ai][bj][m][0][1], acc[ai][bj][m][0][2], acc[ai][bj][m][0][3], acc[ai][bj][m][1][0], acc[ai][bj][m][1][1], acc[ai][bj][m][1][2], acc[ai][bj][m][1][3]};
;                     if (GATED) { const u32x4 pp = *(const u32x4*)(PP + off);
;                         const float pv[8] = {bflo(pp.x), bfhi(pp.x), bflo(pp.y), bfhi(pp.y), bflo(pp.z), bfhi(pp.z), bflo(pp.w), bfhi(pp.w)};
; #pragma unroll
;                         for (int e = 0; e < 8; ++e) av[e] = fast_sigmoid(av[e] * rs) * pv[e]; }
;                     else {
; #pragma unroll
;                         for (int e = 0; e < 8; ++e) av[e] *= alpha; }
;                     float lo[8];
; #pragma unroll
;                     for (int e = 0; e < 8; ++e) { hv[e] += av[e]; sq += hv[e] * hv[e]; }
;                     u32x4 wh; wh.x = pk2(hv[0], hv[1]); wh.y = pk2(hv[2], hv[3]); wh.z = pk2(hv[4], hv[5]); wh.w = pk2(hv[6], hv[7]);
;                     lo[0] = hv[0] - bflo(wh.x); lo[1] = hv[1] - bfhi(wh.x); lo[2] = hv[2] - bflo(wh.y); lo[3] = hv[3] - bfhi(wh.y);
;                     lo[4] = hv[4] - bflo(wh.z); lo[5] = hv[5] - bfhi(wh.z); lo[6] = hv[6] - bflo(wh.w); lo[7] = hv[7] - bfhi(wh.w);
;                     u32x4 wl; wl.x = pk2(lo[0], lo[1]); wl.y = pk2(lo[2], lo[3]); wl.z = pk2(lo[4], lo[5]); wl.w = pk2(lo[6], lo[7]);
;                     *(u32x4*)(HO + off) = wh; *(u32x4*)(LO + off) = wl;
;                 }
;                 sq += __shfl_xor(sq, 16); sq += __shfl_xor(sq, 32);
;                 if (fq == 0) ssq_out[(size_t)row * 16 + 4 * u.pn + wc] = sq;
	s_nop 0
	v_mov_b32_e32 v30, v234
	v_mov_b32_e32 v31, v235
	v_mov_b32_e32 v32, v236
	v_mov_b32_e32 v33, v237
	v_rcp_f32_e32 v54, v22
	s_waitcnt vmcnt(2)
	s_nop 0
	v_mov_b32_e32 v34, v230
	v_mov_b32_e32 v35, v231
	v_mov_b32_e32 v36, v232
	v_mov_b32_e32 v37, v233
	v_mul_f32_e32 v22, v23, v56
	v_mul_f32_e32 v22, 0xbfb8aa3b, v22
	v_exp_f32_e32 v22, v22
	s_nop 0
	v_add_f32_e32 v22, 1.0, v22
	v_rcp_f32_e32 v55, v22
	v_mul_f32_e32 v22, v24, v56
	v_rcp_f32_e32 v24, v18
	v_mul_f32_e32 v18, v19, v56
	v_mul_f32_e32 v22, 0xbfb8aa3b, v22
	v_mul_f32_e32 v18, 0xbfb8aa3b, v18
	v_exp_f32_e32 v22, v22
	v_exp_f32_e32 v18, v18
	v_add_f32_e32 v22, 1.0, v22
	v_add_f32_e32 v18, 1.0, v18
	v_rcp_f32_e32 v52, v22
	v_mul_f32_e32 v22, v25, v56
	v_rcp_f32_e32 v25, v18
	v_mul_f32_e32 v18, v20, v56
	v_mul_f32_e32 v22, 0xbfb8aa3b, v22
	v_mul_f32_e32 v18, 0xbfb8aa3b, v18
	v_exp_f32_e32 v22, v22
	v_exp_f32_e32 v18, v18
	v_add_f32_e32 v22, 1.0, v22
	v_add_f32_e32 v18, 1.0, v18
	v_rcp_f32_e32 v53, v22
	v_rcp_f32_e32 v22, v18
	v_mul_f32_e32 v18, v21, v56
	v_mul_f32_e32 v18, 0xbfb8aa3b, v18
	v_exp_f32_e32 v18, v18
	s_waitcnt vmcnt(5)
	v_and_b32_e32 v19, 0xffff0000, v26
	v_add_f32_e32 v18, 1.0, v18
	v_rcp_f32_e32 v23, v18
	v_lshlrev_b32_e32 v18, 16, v26
	s_waitcnt vmcnt(5)
	v_lshlrev_b32_e32 v20, 16, v30
	v_and_b32_e32 v21, 0xffff0000, v30
	v_pk_add_f32 v[18:19], v[18:19], v[20:21]
	s_waitcnt vmcnt(5)
	v_lshlrev_b32_e32 v20, 16, v34
	v_and_b32_e32 v21, 0xffff0000, v34
	v_pk_fma_f32 v[20:21], v[54:55], v[20:21], v[18:19]
	v_lshlrev_b32_e32 v26, 16, v31
	v_cvt_pk_bf16_f32 v18, v20, v21
	v_lshlrev_b32_e32 v54, 16, v18
	v_and_b32_e32 v55, 0xffff0000, v18
	v_pk_mul_f32 v[56:57], v[20:21], v[20:21]
	v_pk_add_f32 v[54:55], v[20:21], v[54:55] neg_lo:[0,1] neg_hi:[0,1]
	v_lshlrev_b32_e32 v20, 16, v27
	v_and_b32_e32 v21, 0xffff0000, v27
	v_and_b32_e32 v27, 0xffff0000, v31
	v_pk_add_f32 v[20:21], v[20:21], v[26:27]
	v_lshlrev_b32_e32 v26, 16, v35
	v_and_b32_e32 v27, 0xffff0000, v35
	v_pk_fma_f32 v[20:21], v[52:53], v[26:27], v[20:21]
	v_lshlrev_b32_e32 v34, 16, v32
	v_cvt_pk_bf16_f32 v19, v20, v21
	v_lshlrev_b32_e32 v30, 16, v19
	v_and_b32_e32 v31, 0xffff0000, v19
	v_pk_mul_f32 v[26:27], v[20:21], v[20:21]
	v_pk_add_f32 v[30:31], v[20:21], v[30:31] neg_lo:[0,1] neg_hi:[0,1]
	v_lshlrev_b32_e32 v20, 16, v28
	v_and_b32_e32 v21, 0xffff0000, v28
	v_and_b32_e32 v35, 0xffff0000, v32
	v_pk_add_f32 v[20:21], v[20:21], v[34:35]
	v_lshlrev_b32_e32 v34, 16, v36
	v_and_b32_e32 v35, 0xffff0000, v36
	v_pk_fma_f32 v[24:25], v[24:25], v[34:35], v[20:21]
	v_add_f32_e32 v21, v42, v43
	v_add_f32_e32 v21, v44, v21
	v_add_f32_e32 v21, v45, v21
	v_add_f32_e32 v21, v46, v21
	v_add_f32_e32 v21, v47, v21
	v_add_f32_e32 v21, v48, v21
	v_add_f32_e32 v21, v49, v21
	v_add_f32_e32 v21, v56, v21
	v_add_f32_e32 v21, v57, v21
	v_lshlrev_b32_e32 v28, 16, v29
	v_and_b32_e32 v29, 0xffff0000, v29
	v_lshlrev_b32_e32 v32, 16, v33
	v_and_b32_e32 v33, 0xffff0000, v33
	v_add_f32_e32 v21, v26, v21
	v_pk_mul_f32 v[34:35], v[24:25], v[24:25]
	v_pk_add_f32 v[28:29], v[28:29], v[32:33]
	v_lshlrev_b32_e32 v32, 16, v37
	v_and_b32_e32 v33, 0xffff0000, v37
	v_add_f32_e32 v21, v27, v21
	v_pk_fma_f32 v[22:23], v[22:23], v[32:33], v[28:29]
	v_add_f32_e32 v21, v34, v21
	v_pk_mul_f32 v[28:29], v[22:23], v[22:23]
	v_add_f32_e32 v21, v35, v21
	v_add_f32_e32 v21, v28, v21
	v_cvt_pk_bf16_f32 v20, v24, v25
	v_add_f32_e32 v28, v29, v21
	v_cvt_pk_bf16_f32 v21, v22, v23
	v_lshlrev_b32_e32 v52, 16, v20
	v_and_b32_e32 v53, 0xffff0000, v20
	v_lshlrev_b32_e32 v26, 16, v21
	v_and_b32_e32 v27, 0xffff0000, v21
	v_pk_add_f32 v[24:25], v[24:25], v[52:53] neg_lo:[0,1] neg_hi:[0,1]
	v_pk_add_f32 v[26:27], v[22:23], v[26:27] neg_lo:[0,1] neg_hi:[0,1]
	v_cvt_pk_bf16_f32 v24, v24, v25
	v_cvt_pk_bf16_f32 v25, v26, v27
	v_lshl_add_u64 v[26:27], s[58:59], 0, v[40:41]
	v_cvt_pk_bf16_f32 v22, v54, v55
	v_cvt_pk_bf16_f32 v23, v30, v31
	global_store_dwordx4 v[26:27], v[18:21], off
	global_store_dwordx4 v[50:51], v[22:25], off
	v_mov_b32_e32 v18, v28
	s_nop 1
	v_permlane16_swap_b32_e32 v28, v18
	s_waitcnt lgkmcnt(0)
	v_add_f32_e32 v18, v28, v18
	ds_bpermute_b32 v19, v145, v18
	s_and_saveexec_b64 s[12:13], s[0:1]
	s_cbranch_execz .LBB0_1352
	v_readlane_b32 s44, v250, 8
	v_readlane_b32 s46, v250, 10
	v_readlane_b32 s47, v250, 11
	s_waitcnt lgkmcnt(0)
	v_add_f32_e32 v20, v18, v19
	s_lshl_b32 s40, s25, 2
	v_lshl_add_u64 v[18:19], s[46:47], 0, v[38:39]
	v_lshl_add_u64 v[18:19], s[54:55], 2, v[18:19]
	v_lshl_add_u64 v[18:19], v[18:19], 0, s[40:41]
	v_readlane_b32 s45, v250, 9
	global_store_dword v[18:19], v20, off
; __device__ __forceinline__ float row_ssq(const float* part, int pitch, int n4, int row, int fq) {
;     __device__ __forceinline__ void operator()(const f32x4 (&acc)[2][2][4][2], const Unit& u, int wr, int wc, int fr, int fq) const {
;     ...
;                 const int row = row0 + ai * HALF + m * 16;
;                 float rs = 0.f; if (GATED) rs = rsqrtf(row_ssq(ssq_in, 16, 4, row, fq) * (1.f / 1024.f) + EPS);
;                 float sq = 0.f;
; #pragma unroll
;                 for (int bj = 0; bj < 2; ++bj) {
;                     const size_t off = (size_t)row * DM + col0 + bj * HALF;
;                     const u32x4 hh = *(const u32x4*)(HI + off), ll = *(const u32x4*)(LO + off);
;                     float hv[8] = {bflo(hh.x) + bflo(ll.x), bfhi(hh.x) + bfhi(ll.x), bflo(hh.y) + bflo(ll.y), bfhi(hh.y) + bfhi(ll.y),
;                                    bflo(hh.z) + bflo(ll.z), bfhi(hh.z) + bfhi(ll.z), bflo(hh.w) + bflo(ll.w), bfhi(hh.w) + bfhi(ll.w)};
;                     float av[8] = {acc[ai][bj][m][0][0], acc[ai][bj][m][0][1], acc[ai][bj][m][0][2], acc[ai][bj][m][0][3], acc[ai][bj][m][1][0], acc[ai][bj][m][1][1], acc[ai][bj][m][1][2], acc[ai][bj][m][1][3]};
;                     if (GATED) { const u32x4 pp = *(const u32x4*)(PP + off);
;                         const float pv[8] = {bflo(pp.x), bfhi(pp.x), bflo(pp.y), bfhi(pp.y), bflo(pp.z), bfhi(pp.z), bflo(pp.w), bfhi(pp.w)};
; #pragma unroll
;                         for (int e = 0; e < 8; ++e) av[e] = fast_sigmoid(av[e] * rs) * pv[e]; }
;                     else {
; #pragma unroll
;                         for (int e = 0; e < 8; ++e) av[e] *= alpha; }
;                     float lo[8];
; #pragma unroll
;                     for (int e = 0; e < 8; ++e) { hv[e] += av[e]; sq += hv[e] * hv[e]; }
;                     u32x4 wh; wh.x = pk2(hv[0], hv[1]); wh.y = pk2(hv[2], hv[3]); wh.z = pk2(hv[4], hv[5]); wh.w = pk2(hv[6], hv[7]);
;                     lo[0] = hv[0] - bflo(wh.x); lo[1] = hv[1] - bfhi(wh.x); lo[2] = hv[2] - bflo(wh.y); lo[3] = hv[3] - bfhi(wh.y);
;                     lo[4] = hv[4] - bflo(wh.z); lo[5] = hv[5] - bfhi(wh.z); lo[6] = hv[6] - bflo(wh.w); lo[7] = hv[7] - bfhi(wh.w);
;                     u32x4 wl; wl.x = pk2(lo[0], lo[1]); wl.y = pk2(lo[2], lo[3]); wl.z = pk2(lo[4], lo[5]); wl.w = pk2(lo[6], lo[7]);
;                     *(u32x4*)(HO + off) = wh; *(u32x4*)(LO + off) = wl;
.LBB0_1352:
	s_or_b64 exec, exec, s[12:13]
	v_add_u32_e32 v24, 0xb0, v144
	v_ashrrev_i32_e32 v25, 31, v24
	v_lshlrev_b64 v[22:23], 6, v[24:25]
	s_waitcnt lgkmcnt(0)
	v_lshl_add_u64 v[18:19], v[136:137], 0, v[22:23]
	global_load_dwordx4 v[18:21], v[18:19], off
	v_readlane_b32 s10, v253, 35
	v_readlane_b32 s11, v253, 36
	v_readlane_b32 s6, v250, 49
	v_readlane_b32 s7, v250, 50
	s_waitcnt vmcnt(0)
	v_mov_b32_e32 v26, v19
	v_mov_b32_e32 v27, v20
	v_mov_b32_e32 v19, v21
	v_pk_add_f32 v[18:19], v[26:27], v[18:19]
	s_nop 0
	v_add_f32_e32 v18, v18, v19
	v_mov_b32_e32 v19, v18
	s_nop 1
	v_permlane16_swap_b32_e32 v18, v19
	s_waitcnt lgkmcnt(0)
	v_add_f32_e32 v18, v18, v19
	v_mov_b32_e32 v19, v18
	s_nop 1
	v_permlane32_swap_b32_e32 v18, v19
	s_waitcnt lgkmcnt(0)
	v_add_f32_e32 v18, v18, v19
	v_fmamk_f32 v18, v18, 0x3a800000, v239
	v_cmp_gt_f32_e32 vcc, s16, v18
	v_mul_f32_e32 v19, 0x4b800000, v18
	s_nop 0
	v_cndmask_b32_e32 v18, v18, v19, vcc
	v_rsq_f32_e32 v18, v18
	s_nop 0
	v_mul_f32_e32 v19, 0x45800000, v18
	v_cndmask_b32_e32 v40, v18, v19, vcc
	v_lshlrev_b64 v[18:19], 10, v[24:25]
	v_lshl_add_u64 v[18:19], v[18:19], 0, v[142:143]
	v_lshlrev_b64 v[24:25], 1, v[18:19]
	v_lshl_add_u64 v[18:19], s[10:11], 0, v[24:25]
	v_lshl_add_u64 v[20:21], s[14:15], 0, v[24:25]
	global_load_dwordx4 v[30:33], v[18:19], off
	global_load_dwordx4 v[42:45], v[20:21], off
	v_lshl_add_u64 v[18:19], s[6:7], 0, v[24:25]
	global_load_dwordx4 v[34:37], v[18:19], off
	global_load_dwordx4 v[226:229], v24, s[10:11] offset:256
	global_load_dwordx4 v[234:237], v24, s[6:7] offset:256
	global_load_dwordx4 v[230:233], v24, s[14:15] offset:256
	v_mul_f32_e32 v10, v10, v40
	v_mul_f32_e32 v10, 0xbfb8aa3b, v10
	v_exp_f32_e32 v10, v10
	v_mul_f32_e32 v14, v14, v40
	v_mul_f32_e32 v15, v15, v40
	v_mul_f32_e32 v14, 0xbfb8aa3b, v14
	v_add_f32_e32 v10, 1.0, v10
	v_rcp_f32_e32 v20, v10
	v_mul_f32_e32 v10, v11, v40
	v_mul_f32_e32 v10, 0xbfb8aa3b, v10
	v_exp_f32_e32 v10, v10
	v_mul_f32_e32 v15, 0xbfb8aa3b, v15
	v_exp_f32_e32 v14, v14
	v_exp_f32_e32 v15, v15
	v_add_f32_e32 v10, 1.0, v10
	v_rcp_f32_e32 v21, v10
	v_mul_f32_e32 v10, v12, v40
	v_mul_f32_e32 v10, 0xbfb8aa3b, v10
	v_exp_f32_e32 v10, v10
	v_mul_f32_e32 v16, v16, v40
	v_mul_f32_e32 v17, v17, v40
	v_add_f32_e32 v14, 1.0, v14
	v_add_f32_e32 v10, 1.0, v10
	v_rcp_f32_e32 v38, v10
	v_mul_f32_e32 v10, v13, v40
	v_mul_f32_e32 v10, 0xbfb8aa3b, v10
	v_exp_f32_e32 v10, v10
	v_add_f32_e32 v15, 1.0, v15
	v_mul_f32_e32 v16, 0xbfb8aa3b, v16
	v_mul_f32_e32 v17, 0xbfb8aa3b, v17
	v_rcp_f32_e32 v14, v14
	v_rcp_f32_e32 v15, v15
	v_exp_f32_e32 v16, v16
	v_exp_f32_e32 v17, v17
	v_add_f32_e32 v10, 1.0, v10
	v_rcp_f32_e32 v39, v10
	v_add_f32_e32 v16, 1.0, v16
	v_add_f32_e32 v17, 1.0, v17
	v_rcp_f32_e32 v16, v16
	v_rcp_f32_e32 v17, v17
	v_mul_f32_e32 v6, v6, v40
	v_mul_f32_e32 v6, 0xbfb8aa3b, v6
	v_exp_f32_e32 v6, v6
	v_mul_f32_e32 v2, v2, v40
	v_mul_f32_e32 v2, 0xbfb8aa3b, v2
	v_exp_f32_e32 v2, v2
	v_add_f32_e32 v6, 1.0, v6
	v_add_f32_e32 v2, 1.0, v2
	s_waitcnt vmcnt(5)
	v_lshlrev_b32_e32 v10, 16, v30
	v_and_b32_e32 v11, 0xffff0000, v30
	s_waitcnt vmcnt(3)
	v_lshlrev_b32_e32 v12, 16, v34
	v_and_b32_e32 v13, 0xffff0000, v34
	v_pk_add_f32 v[10:11], v[10:11], v[12:13]
	v_lshlrev_b32_e32 v12, 16, v42
	v_and_b32_e32 v13, 0xffff0000, v42
	v_pk_fma_f32 v[12:13], v[14:15], v[12:13], v[10:11]
	v_lshlrev_b32_e32 v28, 16, v35
	v_cvt_pk_bf16_f32 v10, v12, v13
	v_lshlrev_b32_e32 v14, 16, v10
	v_and_b32_e32 v15, 0xffff0000, v10
	v_pk_mul_f32 v[26:27], v[12:13], v[12:13]
	v_pk_add_f32 v[14:15], v[12:13], v[14:15] neg_lo:[0,1] neg_hi:[0,1]
	v_lshlrev_b32_e32 v12, 16, v31
	v_and_b32_e32 v13, 0xffff0000, v31
	v_and_b32_e32 v29, 0xffff0000, v35
	v_pk_add_f32 v[12:13], v[12:13], v[28:29]
	v_lshlrev_b32_e32 v28, 16, v43
	v_and_b32_e32 v29, 0xffff0000, v43
	v_pk_fma_f32 v[12:13], v[16:17], v[28:29], v[12:13]
	v_lshlrev_b32_e32 v30, 16, v36
	v_cvt_pk_bf16_f32 v11, v12, v13
	v_lshlrev_b32_e32 v16, 16, v11
	v_and_b32_e32 v17, 0xffff0000, v11
	v_pk_mul_f32 v[28:29], v[12:13], v[12:13]
	v_pk_add_f32 v[16:17], v[12:13], v[16:17] neg_lo:[0,1] neg_hi:[0,1]
	v_lshlrev_b32_e32 v12, 16, v32
	v_and_b32_e32 v13, 0xffff0000, v32
	v_and_b32_e32 v31, 0xffff0000, v36
	v_pk_add_f32 v[12:13], v[12:13], v[30:31]
	v_lshlrev_b32_e32 v30, 16, v44
	v_and_b32_e32 v31, 0xffff0000, v44
	v_pk_fma_f32 v[20:21], v[20:21], v[30:31], v[12:13]
	v_lshlrev_b32_e32 v32, 16, v33
	v_cvt_pk_bf16_f32 v12, v20, v21
	v_lshlrev_b32_e32 v34, 16, v12
	v_and_b32_e32 v35, 0xffff0000, v12
	v_pk_mul_f32 v[30:31], v[20:21], v[20:21]
	v_pk_add_f32 v[20:21], v[20:21], v[34:35] neg_lo:[0,1] neg_hi:[0,1]
	v_and_b32_e32 v33, 0xffff0000, v33
	v_lshlrev_b32_e32 v34, 16, v37
	v_and_b32_e32 v35, 0xffff0000, v37
	v_pk_add_f32 v[32:33], v[32:33], v[34:35]
	v_lshlrev_b32_e32 v34, 16, v45
	v_and_b32_e32 v35, 0xffff0000, v45
	v_pk_fma_f32 v[34:35], v[38:39], v[34:35], v[32:33]
	v_cvt_pk_bf16_f32 v14, v14, v15
	v_cvt_pk_bf16_f32 v13, v34, v35
	v_lshlrev_b32_e32 v36, 16, v13
	v_and_b32_e32 v37, 0xffff0000, v13
	v_pk_mul_f32 v[32:33], v[34:35], v[34:35]
	v_pk_add_f32 v[34:35], v[34:35], v[36:37] neg_lo:[0,1] neg_hi:[0,1]
	v_cvt_pk_bf16_f32 v15, v16, v17
	v_cvt_pk_bf16_f32 v16, v20, v21
	v_lshl_add_u64 v[20:21], s[58:59], 0, v[24:25]
	v_or_b32_e32 v24, 0x100, v24
	v_cvt_pk_bf16_f32 v17, v34, v35
	global_store_dwordx4 v[20:21], v[10:13], off
	global_store_dwordx4 v[18:19], v[14:17], off
	v_lshl_add_u64 v[34:35], s[6:7], 0, v[24:25]
	v_lshl_add_u64 v[10:11], s[10:11], 0, v[24:25]
	s_waitcnt vmcnt(4)
; __device__ __forceinline__ float bflo(unsigned u) { return __uint_as_float(u << 16); }
;     __device__ __forceinline__ void operator()(const f32x4 (&acc)[2][2][4][2], const Unit& u, int wr, int wc, int fr, int fq) const {
;     ...
;                 for (int bj = 0; bj < 2; ++bj) {
;                     const size_t off = (size_t)row * DM + col0 + bj * HALF;
;                     const u32x4 hh = *(const u32x4*)(HI + off), ll = *(const u32x4*)(LO + off);
;                     float hv[8] = {bflo(hh.x) + bflo(ll.x), bfhi(hh.x) + bfhi(ll.x), bflo(hh.y) + bflo(ll.y), bfhi(hh.y) + bfhi(ll.y),
;                                    bflo(hh.z) + bflo(ll.z), bfhi(hh.z) + bfhi(ll.z), bflo(hh.w) + bflo(ll.w), bfhi(hh.w) + bfhi(ll.w)};
;                     float av[8] = {acc[ai][bj][m][0][0], acc[ai][bj][m][0][1], acc[ai][bj][m][0][2], acc[ai][bj][m][0][3], acc[ai][bj][m][1][0], acc[ai][bj][m][1][1], acc[ai][bj][m][1][2], acc[ai][bj][m][1][3]};
;                     if (GATED) { const u32x4 pp = *(const u32x4*)(PP + off);
;                         const float pv[8] = {bflo(pp.x), bfhi(pp.x), bflo(pp.y), bfhi(pp.y), bflo(pp.z), bfhi(pp.z), bflo(pp.w), bfhi(pp.w)};
; #pragma unroll
;                         for (int e = 0; e < 8; ++e) av[e] = fast_sigmoid(av[e] * rs) * pv[e]; }
;                     else {
; #pragma unroll
;                         for (int e = 0; e < 8; ++e) av[e] *= alpha; }
;                     float lo[8];
; #pragma unroll
;                     for (int e = 0; e < 8; ++e) { hv[e] += av[e]; sq += hv[e] * hv[e]; }
;                     u32x4 wh; wh.x = pk2(hv[0], hv[1]); wh.y = pk2(hv[2], hv[3]); wh.z = pk2(hv[4], hv[5]); wh.w = pk2(hv[6], hv[7]);
;                     lo[0] = hv[0] - bflo(wh.x); lo[1] = hv[1] - bfhi(wh.x); lo[2] = hv[2] - bflo(wh.y); lo[3] = hv[3] - bfhi(wh.y);
;                     lo[4] = hv[4] - bflo(wh.z); lo[5] = hv[5] - bfhi(wh.z); lo[6] = hv[6] - bflo(wh.w); lo[7] = hv[7] - bfhi(wh.w);
;                     u32x4 wl; wl.x = pk2(lo[0], lo[1]); wl.y = pk2(lo[2], lo[3]); wl.z = pk2(lo[4], lo[5]); wl.w = pk2(lo[6], lo[7]);
;                     *(u32x4*)(HO + off) = wh; *(u32x4*)(LO + off) = wl;
;                 }
;                 sq += __shfl_xor(sq, 16); sq += __shfl_xor(sq, 32);
;                 if (fq == 0) ssq_out[(size_t)row * 16 + 4 * u.pn + wc] = sq;
	s_nop 0
	v_mov_b32_e32 v10, v226
	v_mov_b32_e32 v11, v227
	v_mov_b32_e32 v12, v228
	v_mov_b32_e32 v13, v229
	v_lshl_add_u64 v[18:19], s[14:15], 0, v[24:25]
	s_waitcnt vmcnt(3)
	s_nop 0
	v_mov_b32_e32 v14, v234
	v_mov_b32_e32 v15, v235
	v_mov_b32_e32 v16, v236
	v_mov_b32_e32 v17, v237
	v_rcp_f32_e32 v38, v6
	s_waitcnt vmcnt(2)
	s_nop 0
	v_mov_b32_e32 v18, v230
	v_mov_b32_e32 v19, v231
	v_mov_b32_e32 v20, v232
	v_mov_b32_e32 v21, v233
	v_mul_f32_e32 v6, v7, v40
	v_mul_f32_e32 v6, 0xbfb8aa3b, v6
	v_exp_f32_e32 v6, v6
	s_nop 0
	v_add_f32_e32 v6, 1.0, v6
	v_rcp_f32_e32 v39, v6
	v_mul_f32_e32 v6, v8, v40
	v_rcp_f32_e32 v8, v2
	v_mul_f32_e32 v2, v3, v40
	v_mul_f32_e32 v6, 0xbfb8aa3b, v6
	v_mul_f32_e32 v2, 0xbfb8aa3b, v2
	v_exp_f32_e32 v6, v6
	v_exp_f32_e32 v2, v2
	v_add_f32_e32 v6, 1.0, v6
	v_add_f32_e32 v2, 1.0, v2
	v_rcp_f32_e32 v36, v6
	v_mul_f32_e32 v6, v9, v40
	v_rcp_f32_e32 v9, v2
	v_mul_f32_e32 v2, v4, v40
	v_mul_f32_e32 v6, 0xbfb8aa3b, v6
	v_mul_f32_e32 v2, 0xbfb8aa3b, v2
	v_exp_f32_e32 v6, v6
	v_exp_f32_e32 v2, v2
	v_add_f32_e32 v6, 1.0, v6
	v_add_f32_e32 v2, 1.0, v2
	v_rcp_f32_e32 v37, v6
	v_rcp_f32_e32 v6, v2
	v_mul_f32_e32 v2, v5, v40
	v_mul_f32_e32 v2, 0xbfb8aa3b, v2
	v_exp_f32_e32 v2, v2
	s_waitcnt vmcnt(5)
	v_and_b32_e32 v3, 0xffff0000, v10
	v_add_f32_e32 v2, 1.0, v2
	v_rcp_f32_e32 v7, v2
	v_lshlrev_b32_e32 v2, 16, v10
	s_waitcnt vmcnt(5)
	v_lshlrev_b32_e32 v4, 16, v14
	v_and_b32_e32 v5, 0xffff0000, v14
	v_pk_add_f32 v[2:3], v[2:3], v[4:5]
	s_waitcnt vmcnt(5)
	v_lshlrev_b32_e32 v4, 16, v18
	v_and_b32_e32 v5, 0xffff0000, v18
	v_pk_fma_f32 v[4:5], v[38:39], v[4:5], v[2:3]
	v_lshlrev_b32_e32 v10, 16, v15
	v_cvt_pk_bf16_f32 v2, v4, v5
	v_lshlrev_b32_e32 v38, 16, v2
	v_and_b32_e32 v39, 0xffff0000, v2
	v_pk_mul_f32 v[40:41], v[4:5], v[4:5]
	v_pk_add_f32 v[38:39], v[4:5], v[38:39] neg_lo:[0,1] neg_hi:[0,1]
	v_lshlrev_b32_e32 v4, 16, v11
	v_and_b32_e32 v5, 0xffff0000, v11
	v_and_b32_e32 v11, 0xffff0000, v15
	v_pk_add_f32 v[4:5], v[4:5], v[10:11]
	v_lshlrev_b32_e32 v10, 16, v19
	v_and_b32_e32 v11, 0xffff0000, v19
	v_pk_fma_f32 v[4:5], v[36:37], v[10:11], v[4:5]
	v_lshlrev_b32_e32 v18, 16, v16
	v_cvt_pk_bf16_f32 v3, v4, v5
	v_lshlrev_b32_e32 v14, 16, v3
	v_and_b32_e32 v15, 0xffff0000, v3
	v_pk_mul_f32 v[10:11], v[4:5], v[4:5]
	v_pk_add_f32 v[14:15], v[4:5], v[14:15] neg_lo:[0,1] neg_hi:[0,1]
	v_lshlrev_b32_e32 v4, 16, v12
	v_and_b32_e32 v5, 0xffff0000, v12
	v_and_b32_e32 v19, 0xffff0000, v16
	v_pk_add_f32 v[4:5], v[4:5], v[18:19]
	v_lshlrev_b32_e32 v18, 16, v20
	v_and_b32_e32 v19, 0xffff0000, v20
	v_pk_fma_f32 v[8:9], v[8:9], v[18:19], v[4:5]
	v_add_f32_e32 v5, v26, v27
	v_add_f32_e32 v5, v28, v5
	v_add_f32_e32 v5, v29, v5
	v_add_f32_e32 v5, v30, v5
	v_add_f32_e32 v5, v31, v5
	v_add_f32_e32 v5, v32, v5
	v_add_f32_e32 v5, v33, v5
	v_add_f32_e32 v5, v40, v5
	v_add_f32_e32 v5, v41, v5
	v_lshlrev_b32_e32 v12, 16, v13
	v_and_b32_e32 v13, 0xffff0000, v13
	v_lshlrev_b32_e32 v16, 16, v17
	v_and_b32_e32 v17, 0xffff0000, v17
	v_add_f32_e32 v5, v10, v5
	v_pk_mul_f32 v[18:19], v[8:9], v[8:9]
	v_pk_add_f32 v[12:13], v[12:13], v[16:17]
	v_lshlrev_b32_e32 v16, 16, v21
	v_and_b32_e32 v17, 0xffff0000, v21
	v_add_f32_e32 v5, v11, v5
	v_pk_fma_f32 v[6:7], v[6:7], v[16:17], v[12:13]
	v_add_f32_e32 v5, v18, v5
	v_pk_mul_f32 v[12:13], v[6:7], v[6:7]
	v_add_f32_e32 v5, v19, v5
	v_add_f32_e32 v5, v12, v5
	v_cvt_pk_bf16_f32 v4, v8, v9
	v_add_f32_e32 v12, v13, v5
	v_cvt_pk_bf16_f32 v5, v6, v7
	v_lshlrev_b32_e32 v36, 16, v4
	v_and_b32_e32 v37, 0xffff0000, v4
	v_lshlrev_b32_e32 v10, 16, v5
	v_and_b32_e32 v11, 0xffff0000, v5
	v_pk_add_f32 v[8:9], v[8:9], v[36:37] neg_lo:[0,1] neg_hi:[0,1]
	v_pk_add_f32 v[10:11], v[6:7], v[10:11] neg_lo:[0,1] neg_hi:[0,1]
	v_cvt_pk_bf16_f32 v8, v8, v9
	v_cvt_pk_bf16_f32 v9, v10, v11
	v_lshl_add_u64 v[10:11], s[58:59], 0, v[24:25]
	v_cvt_pk_bf16_f32 v6, v38, v39
	v_cvt_pk_bf16_f32 v7, v14, v15
	global_store_dwordx4 v[10:11], v[2:5], off
	global_store_dwordx4 v[34:35], v[6:9], off
	v_mov_b32_e32 v2, v12
	s_nop 1
	v_permlane16_swap_b32_e32 v12, v2
	s_waitcnt lgkmcnt(0)
	v_add_f32_e32 v2, v12, v2
	ds_bpermute_b32 v3, v145, v2
	s_and_saveexec_b64 s[12:13], s[0:1]
	s_cbranch_execz .LBB0_1354
	v_readlane_b32 s44, v250, 8
	v_readlane_b32 s46, v250, 10
	v_readlane_b32 s47, v250, 11
	s_waitcnt lgkmcnt(0)
	v_add_f32_e32 v4, v2, v3
	s_lshl_b32 s40, s25, 2
	v_lshl_add_u64 v[2:3], s[46:47], 0, v[22:23]
	v_lshl_add_u64 v[2:3], s[54:55], 2, v[2:3]
	v_lshl_add_u64 v[2:3], v[2:3], 0, s[40:41]
	v_readlane_b32 s45, v250, 9
	global_store_dword v[2:3], v4, off
